# stacked: GEMM epilogue row-scale loads hoisted (one wait per tile), attention finalize gain loads hoisted, on top of scan loop rewrite and post fast path
# speedup vs baseline: 1.0135x; 1.0098x over previous
; __device__ __forceinline__ unsigned cvt_pk_bf16(float lo, float hi) { unsigned r; asm volatile("v_cvt_pk_f16_f32 %0, %1, %2" : "=v"(r) : "v"(lo), "v"(hi)); return r; }
;     __device__ __forceinline__ void operator()(const f32x4 (&acc)[2][2][4][2], const Unit& u, int wr, int wc, int fr, int fq) const {
;         const int row0 = u.pm * BM + wr * 64 + fr, col0 = u.pn * HALF + wc * 32 + 8 * fq;
; #pragma unroll
;         for (int ai = 0; ai < 2; ++ai)
; #pragma unroll
;             for (int m = 0; m < 4; ++m) {
;                 const int row = row0 + ai * HALF + m * 16; const float sc = rs[row];
;                 const float sc2 = sc * sc, nsl = -1.4426950408889634f * sc;
;                 bf16_t* rowp = O + (size_t)row * ldc + col0;
;                 float h[8];
; #pragma unroll
;                 for (int n = 0; n < 2; ++n)
; #pragma unroll
;                     for (int e = 0; e < 4; ++e) { const float g = acc[ai][0][m][n][e], up = acc[ai][1][m][n][e];
;                         h[4 * n + e] = (g * up) * (sc2 * __builtin_amdgcn_rcpf(1.0f + __builtin_amdgcn_exp2f(g * nsl))); }
;                 u32x4 w; w.x = cvt_pk_bf16(h[0], h[1]); w.y = cvt_pk_bf16(h[2], h[3]); w.z = cvt_pk_bf16(h[4], h[5]); w.w = cvt_pk_bf16(h[6], h[7]);
;                 *(u32x4*)rowp = w;
;             }
.LBB0_169:
	v_lshl_add_u32 v146, s22, 8, v1
	v_ashrrev_i32_e32 v147, 31, v146
	v_lshl_add_u64 v[150:151], v[146:147], 2, s[8:9]
	global_load_dword v147, v[150:151], off
	global_load_dword v192, v[150:151], off offset:64
	global_load_dword v194, v[150:151], off offset:128
	global_load_dword v196, v[150:151], off offset:192
	global_load_dword v198, v[150:151], off offset:512
	global_load_dword v200, v[150:151], off offset:576
	global_load_dword v202, v[150:151], off offset:640
	global_load_dword v204, v[150:151], off offset:704
	v_mov_b32_e32 v172, v125
	v_mov_b32_e32 v160, v118
	v_mov_b32_e32 v164, v127
	v_mov_b32_e32 v166, v129
	v_lshl_or_b32 v158, s55, 7, v153
	v_mov_b64_e32 v[148:149], s[6:7]
	v_ashrrev_i32_e32 v159, 31, v158
	v_or_b32_e32 v176, 16, v146
	v_mov_b32_e32 v168, v122
	v_mov_b32_e32 v170, v123
	v_mad_i64_i32 v[174:175], s[24:25], v146, s54, v[148:149]
	v_lshlrev_b64 v[122:123], 1, v[158:159]
	v_ashrrev_i32_e32 v177, 31, v176
	v_lshl_add_u64 v[158:159], v[174:175], 0, v[122:123]
	v_lshl_add_u64 v[174:175], v[176:177], 2, s[8:9]
	s_andn2_b64 vcc, exec, s[2:3]
	s_mov_b64 s[2:3], -1
	s_waitcnt vmcnt(0)
	v_mul_f32_e32 v125, 0xbfb8aa3b, v147
	v_mul_f32_e32 v118, v118, v125
	v_mul_f32_e32 v127, v119, v125
	v_exp_f32_e32 v118, v118
	v_mul_f32_e32 v129, v120, v125
	v_mul_f32_e32 v165, v115, v125
	v_exp_f32_e32 v127, v127
	v_mul_f32_e32 v161, v147, v147
	v_mul_f32_e32 v147, v121, v125
	v_exp_f32_e32 v129, v129
	v_exp_f32_e32 v165, v165
	v_mul_f32_e32 v157, v114, v125
	v_mul_f32_e32 v167, v116, v125
	v_exp_f32_e32 v147, v147
	v_exp_f32_e32 v157, v157
	v_exp_f32_e32 v167, v167
	v_add_f32_e32 v118, 1.0, v118
	v_add_f32_e32 v169, 1.0, v127
	v_rcp_f32_e32 v127, v118
	v_mul_f32_e32 v125, v117, v125
	v_add_f32_e32 v129, 1.0, v129
	v_add_f32_e32 v171, 1.0, v165
	v_rcp_f32_e32 v165, v169
	v_exp_f32_e32 v125, v125
	v_add_f32_e32 v147, 1.0, v147
	v_rcp_f32_e32 v129, v129
	v_add_f32_e32 v157, 1.0, v157
	v_add_f32_e32 v173, 1.0, v167
	v_rcp_f32_e32 v167, v147
	v_rcp_f32_e32 v169, v157
	v_pk_mul_f32 v[126:127], v[160:161], v[126:127]
	v_mov_b32_e32 v160, v119
	v_rcp_f32_e32 v171, v171
	v_pk_mul_f32 v[118:119], v[160:161], v[164:165]
	v_mov_b32_e32 v160, v120
	v_add_f32_e32 v177, 1.0, v125
	v_rcp_f32_e32 v125, v173
	v_mul_f32_e32 v120, v118, v119
	v_pk_mul_f32 v[118:119], v[160:161], v[128:129]
	v_mov_b32_e32 v160, v121
	v_rcp_f32_e32 v173, v177
	v_mul_f32_e32 v121, v118, v119
	v_pk_mul_f32 v[118:119], v[160:161], v[166:167]
	v_mov_b32_e32 v160, v114
	v_mul_f32_e32 v126, v126, v127
	v_cvt_pk_f16_f32 v114, v126, v120
	v_mul_f32_e32 v120, v118, v119
	v_pk_mul_f32 v[118:119], v[160:161], v[168:169]
	v_mov_b32_e32 v160, v115
	v_mul_f32_e32 v126, v118, v119
	v_pk_mul_f32 v[118:119], v[160:161], v[170:171]
	v_mov_b32_e32 v160, v116
	v_mul_f32_e32 v116, v118, v119
	v_pk_mul_f32 v[118:119], v[160:161], v[124:125]
	v_mov_b32_e32 v160, v117
	v_mul_f32_e32 v117, v118, v119
	v_pk_mul_f32 v[118:119], v[160:161], v[172:173]
	v_cvt_pk_f16_f32 v115, v121, v120
	v_cvt_pk_f16_f32 v116, v126, v116
	v_mov_b32_e32 v120, v107
	v_mul_f32_e32 v118, v118, v119
	v_cvt_pk_f16_f32 v117, v117, v118
	global_store_dwordx4 v[158:159], v[114:117], off
	s_nop 0
	v_mov_b32_e32 v124, v109
	v_mov_b32_e32 v114, v102
	v_mov_b32_e32 v116, v111
	v_mov_b32_e32 v118, v113
	v_or_b32_e32 v126, 32, v146
	v_ashrrev_i32_e32 v127, 31, v126
	v_lshl_add_u64 v[158:159], v[126:127], 2, s[8:9]
	v_mad_i64_i32 v[128:129], s[24:25], v176, s54, v[148:149]
	v_lshl_add_u64 v[128:129], v[128:129], 0, v[122:123]
	v_mul_f32_e32 v107, 0xbfb8aa3b, v192
	v_mul_f32_e32 v102, v102, v107
	v_mul_f32_e32 v109, v103, v107
	v_mul_f32_e32 v111, v104, v107
	v_exp_f32_e32 v102, v102
	v_mul_f32_e32 v115, v192, v192
	v_mul_f32_e32 v117, v98, v107
	v_exp_f32_e32 v109, v109
	v_exp_f32_e32 v111, v111
	v_mul_f32_e32 v113, v105, v107
	v_exp_f32_e32 v117, v117
	v_mul_f32_e32 v119, v99, v107
	v_exp_f32_e32 v113, v113
	v_mul_f32_e32 v121, v100, v107
	v_mul_f32_e32 v107, v101, v107
	v_exp_f32_e32 v119, v119
	v_add_f32_e32 v102, 1.0, v102
	v_exp_f32_e32 v107, v107
	v_add_f32_e32 v109, 1.0, v109
	v_add_f32_e32 v125, 1.0, v111
	v_rcp_f32_e32 v111, v102
	v_exp_f32_e32 v121, v121
	v_add_f32_e32 v147, 1.0, v117
	v_rcp_f32_e32 v117, v109
	v_add_f32_e32 v127, 1.0, v113
	v_rcp_f32_e32 v113, v125
	v_add_f32_e32 v157, 1.0, v119
	v_rcp_f32_e32 v119, v127
	v_add_f32_e32 v161, 1.0, v107
	v_rcp_f32_e32 v107, v147
	v_pk_mul_f32 v[110:111], v[114:115], v[110:111]
	v_mov_b32_e32 v114, v103
	v_add_f32_e32 v160, 1.0, v121
	v_rcp_f32_e32 v121, v157
	v_pk_mul_f32 v[102:103], v[114:115], v[116:117]
	v_mov_b32_e32 v114, v104
	v_rcp_f32_e32 v109, v160
	v_mul_f32_e32 v104, v102, v103
	v_pk_mul_f32 v[102:103], v[114:115], v[112:113]
	v_mov_b32_e32 v114, v105
	v_rcp_f32_e32 v125, v161
	v_mul_f32_e32 v105, v102, v103
	v_pk_mul_f32 v[102:103], v[114:115], v[118:119]
	v_mov_b32_e32 v114, v98
	v_mul_f32_e32 v110, v110, v111
	v_cvt_pk_f16_f32 v98, v110, v104
	v_mul_f32_e32 v104, v102, v103
	v_pk_mul_f32 v[102:103], v[114:115], v[106:107]
	v_mov_b32_e32 v114, v99
	v_mul_f32_e32 v106, v102, v103
	v_pk_mul_f32 v[102:103], v[114:115], v[120:121]
	v_mov_b32_e32 v114, v100
	v_mul_f32_e32 v100, v102, v103
	v_pk_mul_f32 v[102:103], v[114:115], v[108:109]
	v_mov_b32_e32 v114, v101
	v_mul_f32_e32 v101, v102, v103
	v_pk_mul_f32 v[102:103], v[114:115], v[124:125]
	v_cvt_pk_f16_f32 v99, v105, v104
	v_cvt_pk_f16_f32 v100, v106, v100
	v_mov_b32_e32 v104, v91
	v_mul_f32_e32 v102, v102, v103
	v_cvt_pk_f16_f32 v101, v101, v102
	global_store_dwordx4 v[128:129], v[98:101], off
	s_nop 0
	v_mov_b32_e32 v106, v93
	v_mov_b32_e32 v98, v86
	v_mov_b32_e32 v100, v95
	v_mov_b32_e32 v102, v97
; __device__ __forceinline__ unsigned cvt_pk_bf16(float lo, float hi) { unsigned r; asm volatile("v_cvt_pk_f16_f32 %0, %1, %2" : "=v"(r) : "v"(lo), "v"(hi)); return r; }
;     __device__ __forceinline__ void operator()(const f32x4 (&acc)[2][2][4][2], const Unit& u, int wr, int wc, int fr, int fq) const {
;     ...
;                 const int row = row0 + ai * HALF + m * 16; const float sc = rs[row];
;                 const float sc2 = sc * sc, nsl = -1.4426950408889634f * sc;
;                 bf16_t* rowp = O + (size_t)row * ldc + col0;
;                 float h[8];
; #pragma unroll
;                 for (int n = 0; n < 2; ++n)
; #pragma unroll
;                     for (int e = 0; e < 4; ++e) { const float g = acc[ai][0][m][n][e], up = acc[ai][1][m][n][e];
;                         h[4 * n + e] = (g * up) * (sc2 * __builtin_amdgcn_rcpf(1.0f + __builtin_amdgcn_exp2f(g * nsl))); }
;                 u32x4 w; w.x = cvt_pk_bf16(h[0], h[1]); w.y = cvt_pk_bf16(h[2], h[3]); w.z = cvt_pk_bf16(h[4], h[5]); w.w = cvt_pk_bf16(h[6], h[7]);
;                 *(u32x4*)rowp = w;
	v_or_b32_e32 v108, 48, v146
	v_ashrrev_i32_e32 v109, 31, v108
	v_lshl_add_u64 v[112:113], v[108:109], 2, s[8:9]
	v_mad_i64_i32 v[110:111], s[24:25], v126, s54, v[148:149]
	v_lshl_add_u64 v[110:111], v[110:111], 0, v[122:123]
	v_mul_f32_e32 v91, 0xbfb8aa3b, v194
	v_mul_f32_e32 v86, v86, v91
	v_mul_f32_e32 v93, v87, v91
	v_mul_f32_e32 v95, v88, v91
	v_exp_f32_e32 v86, v86
	v_mul_f32_e32 v99, v194, v194
	v_mul_f32_e32 v101, v82, v91
	v_exp_f32_e32 v93, v93
	v_exp_f32_e32 v95, v95
	v_mul_f32_e32 v97, v89, v91
	v_exp_f32_e32 v101, v101
	v_mul_f32_e32 v103, v83, v91
	v_exp_f32_e32 v97, v97
	v_mul_f32_e32 v105, v84, v91
	v_mul_f32_e32 v91, v85, v91
	v_exp_f32_e32 v103, v103
	v_add_f32_e32 v86, 1.0, v86
	v_exp_f32_e32 v91, v91
	v_add_f32_e32 v93, 1.0, v93
	v_add_f32_e32 v107, 1.0, v95
	v_rcp_f32_e32 v95, v86
	v_exp_f32_e32 v105, v105
	v_add_f32_e32 v114, 1.0, v101
	v_rcp_f32_e32 v101, v93
	v_add_f32_e32 v109, 1.0, v97
	v_rcp_f32_e32 v97, v107
	v_add_f32_e32 v115, 1.0, v103
	v_rcp_f32_e32 v103, v109
	v_add_f32_e32 v117, 1.0, v91
	v_rcp_f32_e32 v91, v114
	v_pk_mul_f32 v[94:95], v[98:99], v[94:95]
	v_mov_b32_e32 v98, v87
	v_add_f32_e32 v116, 1.0, v105
	v_rcp_f32_e32 v105, v115
	v_pk_mul_f32 v[86:87], v[98:99], v[100:101]
	v_mov_b32_e32 v98, v88
	v_rcp_f32_e32 v93, v116
	v_mul_f32_e32 v88, v86, v87
	v_pk_mul_f32 v[86:87], v[98:99], v[96:97]
	v_mov_b32_e32 v98, v89
	v_rcp_f32_e32 v107, v117
	v_mul_f32_e32 v89, v86, v87
	v_pk_mul_f32 v[86:87], v[98:99], v[102:103]
	v_mov_b32_e32 v98, v82
	v_mul_f32_e32 v94, v94, v95
	v_cvt_pk_f16_f32 v82, v94, v88
	v_mul_f32_e32 v88, v86, v87
	v_pk_mul_f32 v[86:87], v[98:99], v[90:91]
	v_mov_b32_e32 v98, v83
	v_mul_f32_e32 v90, v86, v87
	v_pk_mul_f32 v[86:87], v[98:99], v[104:105]
	v_mov_b32_e32 v98, v84
	v_mul_f32_e32 v84, v86, v87
	v_pk_mul_f32 v[86:87], v[98:99], v[92:93]
	v_mov_b32_e32 v98, v85
	v_mul_f32_e32 v85, v86, v87
	v_pk_mul_f32 v[86:87], v[98:99], v[106:107]
	v_cvt_pk_f16_f32 v83, v89, v88
	v_cvt_pk_f16_f32 v84, v90, v84
	v_mov_b32_e32 v88, v75
	v_mul_f32_e32 v86, v86, v87
	v_cvt_pk_f16_f32 v85, v85, v86
	global_store_dwordx4 v[110:111], v[82:85], off
	s_nop 0
	v_mov_b32_e32 v90, v77
	v_mov_b32_e32 v82, v70
	v_mov_b32_e32 v84, v79
	v_mov_b32_e32 v86, v81
	v_mad_i64_i32 v[92:93], s[24:25], v108, s54, v[148:149]
	v_lshl_add_u64 v[92:93], v[92:93], 0, v[122:123]
	v_mul_f32_e32 v75, 0xbfb8aa3b, v196
	v_mul_f32_e32 v70, v70, v75
	v_mul_f32_e32 v77, v71, v75
	v_mul_f32_e32 v79, v72, v75
	v_exp_f32_e32 v70, v70
	v_mul_f32_e32 v83, v196, v196
	v_mul_f32_e32 v85, v66, v75
	v_exp_f32_e32 v77, v77
	v_exp_f32_e32 v79, v79
	v_mul_f32_e32 v81, v73, v75
	v_exp_f32_e32 v85, v85
	v_mul_f32_e32 v87, v67, v75
	v_exp_f32_e32 v81, v81
	v_mul_f32_e32 v89, v68, v75
	v_mul_f32_e32 v75, v69, v75
	v_exp_f32_e32 v87, v87
	v_add_f32_e32 v70, 1.0, v70
	v_exp_f32_e32 v75, v75
	v_add_f32_e32 v77, 1.0, v77
	v_add_f32_e32 v91, 1.0, v79
	v_rcp_f32_e32 v79, v70
	v_exp_f32_e32 v89, v89
	v_add_f32_e32 v95, 1.0, v85
	v_rcp_f32_e32 v85, v77
	v_add_f32_e32 v94, 1.0, v81
	v_rcp_f32_e32 v81, v91
	v_add_f32_e32 v96, 1.0, v87
	v_rcp_f32_e32 v87, v94
	v_add_f32_e32 v98, 1.0, v75
	v_rcp_f32_e32 v75, v95
	v_pk_mul_f32 v[78:79], v[82:83], v[78:79]
	v_mov_b32_e32 v82, v71
	v_add_f32_e32 v97, 1.0, v89
	v_rcp_f32_e32 v89, v96
	v_pk_mul_f32 v[70:71], v[82:83], v[84:85]
	v_mov_b32_e32 v82, v72
	v_rcp_f32_e32 v77, v97
	v_mul_f32_e32 v72, v70, v71
	v_pk_mul_f32 v[70:71], v[82:83], v[80:81]
	v_mov_b32_e32 v82, v73
	v_rcp_f32_e32 v91, v98
	v_mul_f32_e32 v73, v70, v71
	v_pk_mul_f32 v[70:71], v[82:83], v[86:87]
	v_mov_b32_e32 v82, v66
	v_mul_f32_e32 v78, v78, v79
	v_cvt_pk_f16_f32 v66, v78, v72
	v_mul_f32_e32 v72, v70, v71
	v_pk_mul_f32 v[70:71], v[82:83], v[74:75]
	v_mov_b32_e32 v82, v67
	v_mul_f32_e32 v74, v70, v71
	v_pk_mul_f32 v[70:71], v[82:83], v[88:89]
	v_mov_b32_e32 v82, v68
	v_mul_f32_e32 v68, v70, v71
	v_pk_mul_f32 v[70:71], v[82:83], v[76:77]
	v_mov_b32_e32 v82, v69
	v_mul_f32_e32 v69, v70, v71
	v_pk_mul_f32 v[70:71], v[82:83], v[90:91]
	v_cvt_pk_f16_f32 v67, v73, v72
	v_cvt_pk_f16_f32 v68, v74, v68
	v_mov_b32_e32 v72, v59
	v_mul_f32_e32 v70, v70, v71
	v_cvt_pk_f16_f32 v69, v69, v70
	global_store_dwordx4 v[92:93], v[66:69], off
	s_nop 0
	v_add_u32_e32 v59, 0x80, v146
	v_mad_i64_i32 v[76:77], s[24:25], v59, s54, v[148:149]
	v_mov_b32_e32 v66, v54
	v_mov_b32_e32 v68, v63
	v_mov_b32_e32 v74, v61
	v_mov_b32_e32 v70, v65
	v_lshl_add_u64 v[76:77], v[76:77], 0, v[122:123]
	v_mul_f32_e32 v59, 0xbfb8aa3b, v198
	v_mul_f32_e32 v54, v54, v59
	v_mul_f32_e32 v61, v55, v59
	v_mul_f32_e32 v63, v56, v59
	v_exp_f32_e32 v54, v54
	v_mul_f32_e32 v67, v198, v198
	v_mul_f32_e32 v69, v50, v59
	v_exp_f32_e32 v61, v61
	v_exp_f32_e32 v63, v63
	v_mul_f32_e32 v65, v57, v59
	v_exp_f32_e32 v69, v69
	v_mul_f32_e32 v71, v51, v59
	v_exp_f32_e32 v65, v65
	v_mul_f32_e32 v73, v52, v59
	v_mul_f32_e32 v59, v53, v59
	v_exp_f32_e32 v71, v71
	v_add_f32_e32 v54, 1.0, v54
	v_exp_f32_e32 v59, v59
	v_add_f32_e32 v61, 1.0, v61
	v_add_f32_e32 v75, 1.0, v63
	v_rcp_f32_e32 v63, v54
	v_exp_f32_e32 v73, v73
	v_add_f32_e32 v79, 1.0, v69
	v_rcp_f32_e32 v69, v61
	v_add_f32_e32 v78, 1.0, v65
	v_rcp_f32_e32 v65, v75
	v_add_f32_e32 v80, 1.0, v71
	v_rcp_f32_e32 v71, v78
	v_add_f32_e32 v82, 1.0, v59
	v_rcp_f32_e32 v59, v79
	v_pk_mul_f32 v[62:63], v[66:67], v[62:63]
	v_mov_b32_e32 v66, v55
	v_add_f32_e32 v81, 1.0, v73
	v_rcp_f32_e32 v73, v80
	v_pk_mul_f32 v[54:55], v[66:67], v[68:69]
	v_mov_b32_e32 v66, v56
	v_rcp_f32_e32 v61, v81
	v_mul_f32_e32 v56, v54, v55
	v_pk_mul_f32 v[54:55], v[66:67], v[64:65]
	v_mov_b32_e32 v66, v57
	v_rcp_f32_e32 v75, v82
	v_mul_f32_e32 v57, v54, v55
	v_pk_mul_f32 v[54:55], v[66:67], v[70:71]
; __device__ __forceinline__ unsigned cvt_pk_bf16(float lo, float hi) { unsigned r; asm volatile("v_cvt_pk_f16_f32 %0, %1, %2" : "=v"(r) : "v"(lo), "v"(hi)); return r; }
;     __device__ __forceinline__ void operator()(const f32x4 (&acc)[2][2][4][2], const Unit& u, int wr, int wc, int fr, int fq) const {
;     ...
;                 const int row = row0 + ai * HALF + m * 16; const float sc = rs[row];
;                 const float sc2 = sc * sc, nsl = -1.4426950408889634f * sc;
;                 bf16_t* rowp = O + (size_t)row * ldc + col0;
;                 float h[8];
; #pragma unroll
;                 for (int n = 0; n < 2; ++n)
; #pragma unroll
;                     for (int e = 0; e < 4; ++e) { const float g = acc[ai][0][m][n][e], up = acc[ai][1][m][n][e];
;                         h[4 * n + e] = (g * up) * (sc2 * __builtin_amdgcn_rcpf(1.0f + __builtin_amdgcn_exp2f(g * nsl))); }
;                 u32x4 w; w.x = cvt_pk_bf16(h[0], h[1]); w.y = cvt_pk_bf16(h[2], h[3]); w.z = cvt_pk_bf16(h[4], h[5]); w.w = cvt_pk_bf16(h[6], h[7]);
;                 *(u32x4*)rowp = w;
	v_mov_b32_e32 v66, v50
	v_mul_f32_e32 v62, v62, v63
	v_cvt_pk_f16_f32 v50, v62, v56
	v_mul_f32_e32 v56, v54, v55
	v_pk_mul_f32 v[54:55], v[66:67], v[58:59]
	v_mov_b32_e32 v66, v51
	v_mul_f32_e32 v58, v54, v55
	v_pk_mul_f32 v[54:55], v[66:67], v[72:73]
	v_mov_b32_e32 v66, v52
	v_mul_f32_e32 v52, v54, v55
	v_pk_mul_f32 v[54:55], v[66:67], v[60:61]
	v_mov_b32_e32 v66, v53
	v_mul_f32_e32 v53, v54, v55
	v_pk_mul_f32 v[54:55], v[66:67], v[74:75]
	v_cvt_pk_f16_f32 v51, v57, v56
	v_cvt_pk_f16_f32 v52, v58, v52
	v_mov_b32_e32 v56, v43
	v_mul_f32_e32 v54, v54, v55
	v_cvt_pk_f16_f32 v53, v53, v54
	global_store_dwordx4 v[76:77], v[50:53], off
	s_nop 0
	v_add_u32_e32 v43, 0x90, v146
	v_mad_i64_i32 v[60:61], s[24:25], v43, s54, v[148:149]
	v_mov_b32_e32 v50, v38
	v_mov_b32_e32 v52, v47
	v_mov_b32_e32 v58, v45
	v_mov_b32_e32 v54, v49
	v_lshl_add_u64 v[60:61], v[60:61], 0, v[122:123]
	v_mul_f32_e32 v43, 0xbfb8aa3b, v200
	v_mul_f32_e32 v38, v38, v43
	v_mul_f32_e32 v45, v39, v43
	v_mul_f32_e32 v47, v40, v43
	v_exp_f32_e32 v38, v38
	v_mul_f32_e32 v51, v200, v200
	v_mul_f32_e32 v53, v34, v43
	v_exp_f32_e32 v45, v45
	v_exp_f32_e32 v47, v47
	v_mul_f32_e32 v49, v41, v43
	v_exp_f32_e32 v53, v53
	v_mul_f32_e32 v55, v35, v43
	v_exp_f32_e32 v49, v49
	v_mul_f32_e32 v57, v36, v43
	v_mul_f32_e32 v43, v37, v43
	v_exp_f32_e32 v55, v55
	v_add_f32_e32 v38, 1.0, v38
	v_exp_f32_e32 v43, v43
	v_add_f32_e32 v45, 1.0, v45
	v_add_f32_e32 v59, 1.0, v47
	v_rcp_f32_e32 v47, v38
	v_exp_f32_e32 v57, v57
	v_add_f32_e32 v63, 1.0, v53
	v_rcp_f32_e32 v53, v45
	v_add_f32_e32 v62, 1.0, v49
	v_rcp_f32_e32 v49, v59
	v_add_f32_e32 v64, 1.0, v55
	v_rcp_f32_e32 v55, v62
	v_add_f32_e32 v66, 1.0, v43
	v_rcp_f32_e32 v43, v63
	v_pk_mul_f32 v[46:47], v[50:51], v[46:47]
	v_mov_b32_e32 v50, v39
	v_add_f32_e32 v65, 1.0, v57
	v_rcp_f32_e32 v57, v64
	v_pk_mul_f32 v[38:39], v[50:51], v[52:53]
	v_mov_b32_e32 v50, v40
	v_rcp_f32_e32 v45, v65
	v_mul_f32_e32 v40, v38, v39
	v_pk_mul_f32 v[38:39], v[50:51], v[48:49]
	v_mov_b32_e32 v50, v41
	v_rcp_f32_e32 v59, v66
	v_mul_f32_e32 v41, v38, v39
	v_pk_mul_f32 v[38:39], v[50:51], v[54:55]
	v_mov_b32_e32 v50, v34
	v_mul_f32_e32 v46, v46, v47
	v_cvt_pk_f16_f32 v34, v46, v40
	v_mul_f32_e32 v40, v38, v39
	v_pk_mul_f32 v[38:39], v[50:51], v[42:43]
	v_mov_b32_e32 v50, v35
	v_mul_f32_e32 v42, v38, v39
	v_pk_mul_f32 v[38:39], v[50:51], v[56:57]
	v_mov_b32_e32 v50, v36
	v_mul_f32_e32 v36, v38, v39
	v_pk_mul_f32 v[38:39], v[50:51], v[44:45]
	v_mov_b32_e32 v50, v37
	v_mul_f32_e32 v37, v38, v39
	v_pk_mul_f32 v[38:39], v[50:51], v[58:59]
	v_cvt_pk_f16_f32 v35, v41, v40
	v_cvt_pk_f16_f32 v36, v42, v36
	v_mov_b32_e32 v40, v27
	v_mul_f32_e32 v38, v38, v39
	v_cvt_pk_f16_f32 v37, v37, v38
	global_store_dwordx4 v[60:61], v[34:37], off
	s_nop 0
	v_add_u32_e32 v27, 0xa0, v146
	v_mad_i64_i32 v[44:45], s[24:25], v27, s54, v[148:149]
	v_mov_b32_e32 v34, v22
	v_mov_b32_e32 v36, v31
	v_mov_b32_e32 v42, v29
	v_mov_b32_e32 v38, v33
	v_lshl_add_u64 v[44:45], v[44:45], 0, v[122:123]
	v_mul_f32_e32 v27, 0xbfb8aa3b, v202
	v_mul_f32_e32 v22, v22, v27
	v_mul_f32_e32 v29, v23, v27
	v_mul_f32_e32 v31, v24, v27
	v_exp_f32_e32 v22, v22
	v_mul_f32_e32 v35, v202, v202
	v_mul_f32_e32 v37, v18, v27
	v_exp_f32_e32 v29, v29
	v_exp_f32_e32 v31, v31
	v_mul_f32_e32 v33, v25, v27
	v_exp_f32_e32 v37, v37
	v_mul_f32_e32 v39, v19, v27
	v_exp_f32_e32 v33, v33
	v_mul_f32_e32 v41, v20, v27
	v_mul_f32_e32 v27, v21, v27
	v_exp_f32_e32 v39, v39
	v_add_f32_e32 v22, 1.0, v22
	v_exp_f32_e32 v27, v27
	v_add_f32_e32 v29, 1.0, v29
	v_add_f32_e32 v43, 1.0, v31
	v_rcp_f32_e32 v31, v22
	v_exp_f32_e32 v41, v41
	v_add_f32_e32 v47, 1.0, v37
	v_rcp_f32_e32 v37, v29
	v_add_f32_e32 v46, 1.0, v33
	v_rcp_f32_e32 v33, v43
	v_add_f32_e32 v48, 1.0, v39
	v_rcp_f32_e32 v39, v46
	v_add_f32_e32 v50, 1.0, v27
	v_rcp_f32_e32 v27, v47
	v_pk_mul_f32 v[30:31], v[34:35], v[30:31]
	v_mov_b32_e32 v34, v23
	v_add_f32_e32 v49, 1.0, v41
	v_rcp_f32_e32 v41, v48
	v_pk_mul_f32 v[22:23], v[34:35], v[36:37]
	v_mov_b32_e32 v34, v24
	v_rcp_f32_e32 v29, v49
	v_mul_f32_e32 v24, v22, v23
	v_pk_mul_f32 v[22:23], v[34:35], v[32:33]
	v_mov_b32_e32 v34, v25
	v_rcp_f32_e32 v43, v50
	v_mul_f32_e32 v25, v22, v23
	v_pk_mul_f32 v[22:23], v[34:35], v[38:39]
	v_mov_b32_e32 v34, v18
	v_mul_f32_e32 v30, v30, v31
	v_cvt_pk_f16_f32 v18, v30, v24
	v_mul_f32_e32 v24, v22, v23
	v_pk_mul_f32 v[22:23], v[34:35], v[26:27]
	v_mov_b32_e32 v34, v19
	v_mul_f32_e32 v26, v22, v23
	v_pk_mul_f32 v[22:23], v[34:35], v[40:41]
	v_mov_b32_e32 v34, v20
	v_mul_f32_e32 v20, v22, v23
	v_pk_mul_f32 v[22:23], v[34:35], v[28:29]
	v_mov_b32_e32 v34, v21
	v_mul_f32_e32 v21, v22, v23
	v_pk_mul_f32 v[22:23], v[34:35], v[42:43]
	v_cvt_pk_f16_f32 v19, v25, v24
	v_cvt_pk_f16_f32 v20, v26, v20
	v_mov_b32_e32 v24, v11
	v_mul_f32_e32 v22, v22, v23
	v_cvt_pk_f16_f32 v21, v21, v22
	global_store_dwordx4 v[44:45], v[18:21], off
	s_nop 0
	v_add_u32_e32 v11, 0xb0, v146
	v_mad_i64_i32 v[28:29], s[24:25], v11, s54, v[148:149]
	v_mov_b32_e32 v18, v6
	v_mov_b32_e32 v20, v15
	v_mov_b32_e32 v26, v13
	v_mov_b32_e32 v22, v17
	v_lshl_add_u64 v[28:29], v[28:29], 0, v[122:123]
	v_mul_f32_e32 v11, 0xbfb8aa3b, v204
	v_mul_f32_e32 v6, v6, v11
	v_mul_f32_e32 v13, v7, v11
	v_mul_f32_e32 v15, v8, v11
	v_exp_f32_e32 v6, v6
	v_mul_f32_e32 v19, v204, v204
	v_mul_f32_e32 v21, v2, v11
	v_exp_f32_e32 v13, v13
	v_exp_f32_e32 v15, v15
	v_mul_f32_e32 v17, v9, v11
	v_exp_f32_e32 v21, v21
	v_mul_f32_e32 v23, v3, v11
	v_exp_f32_e32 v17, v17
	v_mul_f32_e32 v25, v4, v11
	v_mul_f32_e32 v11, v5, v11
	v_exp_f32_e32 v23, v23
	v_add_f32_e32 v6, 1.0, v6
	v_exp_f32_e32 v11, v11
	v_add_f32_e32 v13, 1.0, v13
	v_add_f32_e32 v27, 1.0, v15
	v_rcp_f32_e32 v15, v6
	v_exp_f32_e32 v25, v25
	v_add_f32_e32 v31, 1.0, v21
	v_rcp_f32_e32 v21, v13
	v_add_f32_e32 v30, 1.0, v17
	v_rcp_f32_e32 v17, v27
	v_add_f32_e32 v32, 1.0, v23
	v_rcp_f32_e32 v23, v30
	v_add_f32_e32 v34, 1.0, v11
	v_rcp_f32_e32 v11, v31
	v_pk_mul_f32 v[14:15], v[18:19], v[14:15]
	v_mov_b32_e32 v18, v7
	v_add_f32_e32 v33, 1.0, v25
	v_rcp_f32_e32 v25, v32
	v_pk_mul_f32 v[6:7], v[18:19], v[20:21]
	v_mov_b32_e32 v18, v8
	v_rcp_f32_e32 v13, v33
	v_mul_f32_e32 v8, v6, v7
	v_pk_mul_f32 v[6:7], v[18:19], v[16:17]
	v_mov_b32_e32 v18, v9
	v_rcp_f32_e32 v27, v34
	v_mul_f32_e32 v9, v6, v7
	v_pk_mul_f32 v[6:7], v[18:19], v[22:23]
	v_mov_b32_e32 v18, v2
	v_mul_f32_e32 v14, v14, v15
	v_cvt_pk_f16_f32 v2, v14, v8
	v_mul_f32_e32 v8, v6, v7
	v_pk_mul_f32 v[6:7], v[18:19], v[10:11]
	v_mov_b32_e32 v18, v3
	v_mul_f32_e32 v10, v6, v7
	v_pk_mul_f32 v[6:7], v[18:19], v[24:25]
	v_mov_b32_e32 v18, v4
	v_mul_f32_e32 v4, v6, v7
	v_pk_mul_f32 v[6:7], v[18:19], v[12:13]
	v_mov_b32_e32 v18, v5
	v_mul_f32_e32 v5, v6, v7
	v_pk_mul_f32 v[6:7], v[18:19], v[26:27]
	v_cvt_pk_f16_f32 v3, v9, v8
	v_cvt_pk_f16_f32 v4, v10, v4
	s_nop 0
	v_mul_f32_e32 v6, v6, v7
	v_cvt_pk_f16_f32 v5, v5, v6
	global_store_dwordx4 v[28:29], v[2:5], off
	s_cbranch_vccnz .LBB0_162
	s_andn2_b64 vcc, exec, s[4:5]
	s_cbranch_vccnz .LBB0_161
	s_barrier
	s_branch .LBB0_161

; __device__ __forceinline__ unsigned cvt_pk_bf16(float lo, float hi) { unsigned r; asm volatile("v_cvt_pk_f16_f32 %0, %1, %2" : "=v"(r) : "v"(lo), "v"(hi)); return r; }
;     __device__ __forceinline__ void operator()(const f32x4 (&acc)[2][2][4][2], const Unit& u, int wr, int wc, int fr, int fq) const {
;         int colt = u.pn * BM; bf16_t* base; int ldc;
;         if (colt < 1024) { base = QK; ldc = 1024; } else { base = PRW; ldc = 1792; colt -= 1024; }
;         const int row0 = u.pm * BM + wr * 64 + fr, col0 = colt + wc * 32 + 8 * fq;
; #pragma unroll
;         for (int ai = 0; ai < 2; ++ai)
; #pragma unroll
;             for (int m = 0; m < 4; ++m) {
;                 const int row = row0 + ai * HALF + m * 16; const float sc = rs[row];
;                 bf16_t* rowp = base + (size_t)row * ldc + col0;
; #pragma unroll
;                 for (int bj = 0; bj < 2; ++bj) { const f32x4 v0 = acc[ai][bj][m][0] * sc, v1 = acc[ai][bj][m][1] * sc;
;                     u32x4 w; w.x = cvt_pk_bf16(v0[0], v0[1]); w.y = cvt_pk_bf16(v0[2], v0[3]); w.z = cvt_pk_bf16(v1[0], v1[1]); w.w = cvt_pk_bf16(v1[2], v1[3]);
;                     *(u32x4*)(rowp + bj * HALF) = w; }
;             }
;     }
.LBB0_421:
	v_lshl_add_u32 v138, s20, 8, v159
	v_ashrrev_i32_e32 v139, 31, v138
	v_lshl_add_u64 v[140:141], v[138:139], 2, s[4:5]
	global_load_dword v168, v[140:141], off
	global_load_dword v192, v[140:141], off offset:64
	global_load_dword v194, v[140:141], off offset:128
	global_load_dword v196, v[140:141], off offset:192
	global_load_dword v198, v[140:141], off offset:512
	global_load_dword v200, v[140:141], off offset:576
	global_load_dword v202, v[140:141], off offset:640
	global_load_dword v204, v[140:141], off offset:704
	s_lshl_b32 s15, s54, 8
	s_add_i32 s20, s15, 0xfffffc00
	s_cmp_lt_i32 s54, 4
	s_cselect_b32 s15, s15, s20
	s_cselect_b32 s20, s53, 0x16c00000
	s_cselect_b32 s13, s52, 0x700
	s_add_u32 s22, s72, s20
	v_or_b32_e32 v142, s15, v161
	s_addc_u32 s23, s73, 0
	v_ashrrev_i32_e32 v143, 31, v142
	v_or_b32_e32 v170, 16, v138
	v_mad_i64_i32 v[174:175], s[24:25], s13, v138, 0
	v_lshl_add_u64 v[142:143], v[142:143], 1, s[22:23]
	v_ashrrev_i32_e32 v171, 31, v170
	v_lshl_add_u64 v[174:175], v[174:175], 1, v[142:143]
	v_lshl_add_u64 v[172:173], v[170:171], 2, s[4:5]
	s_andn2_b64 vcc, exec, s[2:3]
	s_mov_b64 s[2:3], -1
	s_waitcnt vmcnt(0)
	v_pk_mul_f32 v[128:129], v[128:129], v[168:169] op_sel_hi:[1,0]
	v_pk_mul_f32 v[126:127], v[126:127], v[168:169] op_sel_hi:[1,0]
	v_pk_mul_f32 v[124:125], v[124:125], v[168:169] op_sel_hi:[1,0]
	v_pk_mul_f32 v[122:123], v[122:123], v[168:169] op_sel_hi:[1,0]
	v_pk_mul_f32 v[120:121], v[120:121], v[168:169] op_sel_hi:[1,0]
	v_pk_mul_f32 v[118:119], v[118:119], v[168:169] op_sel_hi:[1,0]
	v_pk_mul_f32 v[176:177], v[116:117], v[168:169] op_sel_hi:[1,0]
	v_pk_mul_f32 v[168:169], v[114:115], v[168:169] op_sel_hi:[1,0]
	v_cvt_pk_f16_f32 v114, v126, v127
	v_cvt_pk_f16_f32 v115, v128, v129
	v_cvt_pk_f16_f32 v116, v122, v123
	v_cvt_pk_f16_f32 v117, v124, v125
	global_store_dwordx4 v[174:175], v[114:117], off
	s_nop 1
	v_cvt_pk_f16_f32 v114, v118, v119
	v_cvt_pk_f16_f32 v115, v120, v121
	v_cvt_pk_f16_f32 v116, v168, v169
	v_cvt_pk_f16_f32 v117, v176, v177
	global_store_dwordx4 v[174:175], v[114:117], off offset:256
	s_nop 0
	v_mad_i64_i32 v[120:121], s[22:23], s13, v170, 0
	v_or_b32_e32 v116, 32, v138
	v_ashrrev_i32_e32 v117, 31, v116
	v_lshl_add_u64 v[120:121], v[120:121], 1, v[142:143]
	v_lshl_add_u64 v[118:119], v[116:117], 2, s[4:5]
	v_pk_mul_f32 v[112:113], v[112:113], v[192:193] op_sel_hi:[1,0]
	v_pk_mul_f32 v[110:111], v[110:111], v[192:193] op_sel_hi:[1,0]
	v_pk_mul_f32 v[108:109], v[108:109], v[192:193] op_sel_hi:[1,0]
	v_pk_mul_f32 v[106:107], v[106:107], v[192:193] op_sel_hi:[1,0]
	v_pk_mul_f32 v[104:105], v[104:105], v[192:193] op_sel_hi:[1,0]
	v_pk_mul_f32 v[102:103], v[102:103], v[192:193] op_sel_hi:[1,0]
	v_pk_mul_f32 v[122:123], v[100:101], v[192:193] op_sel_hi:[1,0]
	v_pk_mul_f32 v[114:115], v[98:99], v[192:193] op_sel_hi:[1,0]
	v_cvt_pk_f16_f32 v98, v110, v111
	v_cvt_pk_f16_f32 v99, v112, v113
	v_cvt_pk_f16_f32 v100, v106, v107
	v_cvt_pk_f16_f32 v101, v108, v109
	global_store_dwordx4 v[120:121], v[98:101], off
	s_nop 1
	v_cvt_pk_f16_f32 v98, v102, v103
	v_cvt_pk_f16_f32 v99, v104, v105
	v_cvt_pk_f16_f32 v100, v114, v115
	v_cvt_pk_f16_f32 v101, v122, v123
	global_store_dwordx4 v[120:121], v[98:101], off offset:256
	s_nop 0
	v_mad_i64_i32 v[104:105], s[22:23], s13, v116, 0
	v_or_b32_e32 v100, 48, v138
	v_ashrrev_i32_e32 v101, 31, v100
	v_lshl_add_u64 v[104:105], v[104:105], 1, v[142:143]
	v_lshl_add_u64 v[102:103], v[100:101], 2, s[4:5]
	v_pk_mul_f32 v[96:97], v[96:97], v[194:195] op_sel_hi:[1,0]
	v_pk_mul_f32 v[94:95], v[94:95], v[194:195] op_sel_hi:[1,0]
	v_pk_mul_f32 v[92:93], v[92:93], v[194:195] op_sel_hi:[1,0]
	v_pk_mul_f32 v[90:91], v[90:91], v[194:195] op_sel_hi:[1,0]
	v_pk_mul_f32 v[84:85], v[84:85], v[194:195] op_sel_hi:[1,0]
	v_pk_mul_f32 v[82:83], v[82:83], v[194:195] op_sel_hi:[1,0]
	v_pk_mul_f32 v[106:107], v[76:77], v[194:195] op_sel_hi:[1,0]
	v_pk_mul_f32 v[98:99], v[74:75], v[194:195] op_sel_hi:[1,0]
	v_cvt_pk_f16_f32 v74, v94, v95
	v_cvt_pk_f16_f32 v75, v96, v97
	v_cvt_pk_f16_f32 v76, v90, v91
	v_cvt_pk_f16_f32 v77, v92, v93
	global_store_dwordx4 v[104:105], v[74:77], off
	s_nop 1
	v_cvt_pk_f16_f32 v74, v82, v83
	v_cvt_pk_f16_f32 v75, v84, v85
	v_cvt_pk_f16_f32 v76, v98, v99
	v_cvt_pk_f16_f32 v77, v106, v107
	global_store_dwordx4 v[104:105], v[74:77], off offset:256
	s_nop 0
	v_pk_mul_f32 v[82:83], v[88:89], v[196:197] op_sel_hi:[1,0]
	v_mad_i64_i32 v[76:77], s[22:23], s13, v100, 0
	v_lshl_add_u64 v[76:77], v[76:77], 1, v[142:143]
	v_pk_mul_f32 v[84:85], v[86:87], v[196:197] op_sel_hi:[1,0]
	v_pk_mul_f32 v[80:81], v[80:81], v[196:197] op_sel_hi:[1,0]
	v_pk_mul_f32 v[78:79], v[78:79], v[196:197] op_sel_hi:[1,0]
; __device__ __forceinline__ unsigned cvt_pk_bf16(float lo, float hi) { unsigned r; asm volatile("v_cvt_pk_f16_f32 %0, %1, %2" : "=v"(r) : "v"(lo), "v"(hi)); return r; }
;     __device__ __forceinline__ void operator()(const f32x4 (&acc)[2][2][4][2], const Unit& u, int wr, int wc, int fr, int fq) const {
;     ...
;                 const int row = row0 + ai * HALF + m * 16; const float sc = rs[row];
;                 bf16_t* rowp = base + (size_t)row * ldc + col0;
; #pragma unroll
;                 for (int bj = 0; bj < 2; ++bj) { const f32x4 v0 = acc[ai][bj][m][0] * sc, v1 = acc[ai][bj][m][1] * sc;
;                     u32x4 w; w.x = cvt_pk_bf16(v0[0], v0[1]); w.y = cvt_pk_bf16(v0[2], v0[3]); w.z = cvt_pk_bf16(v1[0], v1[1]); w.w = cvt_pk_bf16(v1[2], v1[3]);
;                     *(u32x4*)(rowp + bj * HALF) = w; }
	v_pk_mul_f32 v[72:73], v[72:73], v[196:197] op_sel_hi:[1,0]
	v_pk_mul_f32 v[70:71], v[70:71], v[196:197] op_sel_hi:[1,0]
	v_pk_mul_f32 v[86:87], v[68:69], v[196:197] op_sel_hi:[1,0]
	v_pk_mul_f32 v[74:75], v[66:67], v[196:197] op_sel_hi:[1,0]
	v_cvt_pk_f16_f32 v66, v84, v85
	v_cvt_pk_f16_f32 v67, v82, v83
	v_cvt_pk_f16_f32 v68, v78, v79
	v_cvt_pk_f16_f32 v69, v80, v81
	global_store_dwordx4 v[76:77], v[66:69], off
	s_nop 1
	v_cvt_pk_f16_f32 v66, v70, v71
	v_cvt_pk_f16_f32 v67, v72, v73
	v_cvt_pk_f16_f32 v68, v74, v75
	v_cvt_pk_f16_f32 v69, v86, v87
	global_store_dwordx4 v[76:77], v[66:69], off offset:256
	s_nop 0
	s_nop 0
	v_add_u32_e32 v67, 0x80, v138
	v_mad_i64_i32 v[68:69], s[22:23], s13, v67, 0
	v_lshl_add_u64 v[68:69], v[68:69], 1, v[142:143]
	v_pk_mul_f32 v[64:65], v[64:65], v[198:199] op_sel_hi:[1,0]
	v_pk_mul_f32 v[62:63], v[62:63], v[198:199] op_sel_hi:[1,0]
	v_pk_mul_f32 v[60:61], v[60:61], v[198:199] op_sel_hi:[1,0]
	v_pk_mul_f32 v[58:59], v[58:59], v[198:199] op_sel_hi:[1,0]
	v_pk_mul_f32 v[56:57], v[56:57], v[198:199] op_sel_hi:[1,0]
	v_pk_mul_f32 v[54:55], v[54:55], v[198:199] op_sel_hi:[1,0]
	v_pk_mul_f32 v[70:71], v[52:53], v[198:199] op_sel_hi:[1,0]
	v_pk_mul_f32 v[66:67], v[50:51], v[198:199] op_sel_hi:[1,0]
	v_cvt_pk_f16_f32 v50, v62, v63
	v_cvt_pk_f16_f32 v51, v64, v65
	v_cvt_pk_f16_f32 v52, v58, v59
	v_cvt_pk_f16_f32 v53, v60, v61
	global_store_dwordx4 v[68:69], v[50:53], off
	s_nop 1
	v_cvt_pk_f16_f32 v50, v54, v55
	v_cvt_pk_f16_f32 v51, v56, v57
	v_cvt_pk_f16_f32 v52, v66, v67
	v_cvt_pk_f16_f32 v53, v70, v71
	global_store_dwordx4 v[68:69], v[50:53], off offset:256
	s_nop 0
	s_nop 0
	v_add_u32_e32 v51, 0x90, v138
	v_mad_i64_i32 v[52:53], s[22:23], s13, v51, 0
	v_lshl_add_u64 v[52:53], v[52:53], 1, v[142:143]
	v_pk_mul_f32 v[48:49], v[48:49], v[200:201] op_sel_hi:[1,0]
	v_pk_mul_f32 v[46:47], v[46:47], v[200:201] op_sel_hi:[1,0]
	v_pk_mul_f32 v[44:45], v[44:45], v[200:201] op_sel_hi:[1,0]
	v_pk_mul_f32 v[42:43], v[42:43], v[200:201] op_sel_hi:[1,0]
	v_pk_mul_f32 v[40:41], v[40:41], v[200:201] op_sel_hi:[1,0]
	v_pk_mul_f32 v[38:39], v[38:39], v[200:201] op_sel_hi:[1,0]
	v_pk_mul_f32 v[54:55], v[36:37], v[200:201] op_sel_hi:[1,0]
	v_pk_mul_f32 v[50:51], v[34:35], v[200:201] op_sel_hi:[1,0]
	v_cvt_pk_f16_f32 v34, v46, v47
	v_cvt_pk_f16_f32 v35, v48, v49
	v_cvt_pk_f16_f32 v36, v42, v43
	v_cvt_pk_f16_f32 v37, v44, v45
	global_store_dwordx4 v[52:53], v[34:37], off
	s_nop 1
	v_cvt_pk_f16_f32 v34, v38, v39
	v_cvt_pk_f16_f32 v35, v40, v41
	v_cvt_pk_f16_f32 v36, v50, v51
	v_cvt_pk_f16_f32 v37, v54, v55
	global_store_dwordx4 v[52:53], v[34:37], off offset:256
	s_nop 0
	s_nop 0
	v_add_u32_e32 v35, 0xa0, v138
	v_mad_i64_i32 v[36:37], s[22:23], s13, v35, 0
	v_lshl_add_u64 v[36:37], v[36:37], 1, v[142:143]
	v_pk_mul_f32 v[32:33], v[32:33], v[202:203] op_sel_hi:[1,0]
	v_pk_mul_f32 v[30:31], v[30:31], v[202:203] op_sel_hi:[1,0]
	v_pk_mul_f32 v[28:29], v[28:29], v[202:203] op_sel_hi:[1,0]
	v_pk_mul_f32 v[26:27], v[26:27], v[202:203] op_sel_hi:[1,0]
	v_pk_mul_f32 v[24:25], v[24:25], v[202:203] op_sel_hi:[1,0]
	v_pk_mul_f32 v[22:23], v[22:23], v[202:203] op_sel_hi:[1,0]
	v_pk_mul_f32 v[38:39], v[20:21], v[202:203] op_sel_hi:[1,0]
	v_pk_mul_f32 v[34:35], v[18:19], v[202:203] op_sel_hi:[1,0]
	v_cvt_pk_f16_f32 v18, v30, v31
	v_cvt_pk_f16_f32 v19, v32, v33
	v_cvt_pk_f16_f32 v20, v26, v27
	v_cvt_pk_f16_f32 v21, v28, v29
	global_store_dwordx4 v[36:37], v[18:21], off
	s_nop 1
	v_cvt_pk_f16_f32 v18, v22, v23
	v_cvt_pk_f16_f32 v19, v24, v25
	v_cvt_pk_f16_f32 v20, v34, v35
	v_cvt_pk_f16_f32 v21, v38, v39
	global_store_dwordx4 v[36:37], v[18:21], off offset:256
	s_nop 0
	s_nop 0
	v_add_u32_e32 v19, 0xb0, v138
	v_mad_i64_i32 v[20:21], s[22:23], s13, v19, 0
	v_lshl_add_u64 v[20:21], v[20:21], 1, v[142:143]
	v_pk_mul_f32 v[16:17], v[16:17], v[204:205] op_sel_hi:[1,0]
	v_pk_mul_f32 v[14:15], v[14:15], v[204:205] op_sel_hi:[1,0]
	v_pk_mul_f32 v[12:13], v[12:13], v[204:205] op_sel_hi:[1,0]
	v_pk_mul_f32 v[10:11], v[10:11], v[204:205] op_sel_hi:[1,0]
	v_pk_mul_f32 v[8:9], v[8:9], v[204:205] op_sel_hi:[1,0]
	v_pk_mul_f32 v[6:7], v[6:7], v[204:205] op_sel_hi:[1,0]
	v_pk_mul_f32 v[22:23], v[4:5], v[204:205] op_sel_hi:[1,0]
	v_pk_mul_f32 v[18:19], v[2:3], v[204:205] op_sel_hi:[1,0]
	v_cvt_pk_f16_f32 v2, v14, v15
	v_cvt_pk_f16_f32 v3, v16, v17
	v_cvt_pk_f16_f32 v4, v10, v11
	v_cvt_pk_f16_f32 v5, v12, v13
	global_store_dwordx4 v[20:21], v[2:5], off
	s_nop 1
	v_cvt_pk_f16_f32 v2, v6, v7
	v_cvt_pk_f16_f32 v3, v8, v9
	v_cvt_pk_f16_f32 v4, v18, v19
	v_cvt_pk_f16_f32 v5, v22, v23
	global_store_dwordx4 v[20:21], v[2:5], off offset:256
	s_cbranch_vccnz .LBB0_414
	s_andn2_b64 vcc, exec, s[6:7]
	s_cbranch_vccnz .LBB0_413
	s_barrier
	s_branch .LBB0_413

; __device__ __forceinline__ unsigned pk2(float lo, float hi) { f32x2 v = {lo, hi}; h16x2 b = __builtin_convertvector(v, h16x2); return __builtin_bit_cast(unsigned, b); }
; __device__ __forceinline__ void attn_fin(const Ctx& F, const float* sbg, int bh, int qt, const f32x16& o0, const f32x16& o1) {
;     ...
;     float ss = 0.f;
; #pragma unroll
;     for (int r = 0; r < 16; ++r) ss += o0[r] * o0[r] + o1[r] * o1[r];
;     ss += __shfl_xor(ss, 32);
;     const float rstd = rsqrtf(ss * (1.f / 64.f) + NORM_EPS);
;     const float* sg = sbg + h * 64;
;     bf16* orow = CAT + ((size_t)b * SEQ + qt * 32 + j) * 1024 + h * 64;
; #pragma unroll
;     for (int q = 0; q < 4; ++q) { const int d = 8 * q + 4 * hi; const f32x4 g0 = *(const f32x4*)(sg + d), g1 = *(const f32x4*)(sg + 32 + d);
;         u32x2 t; t.x = pk2(o0[4 * q] * rstd * g0.x, o0[4 * q + 1] * rstd * g0.y); t.y = pk2(o0[4 * q + 2] * rstd * g0.z, o0[4 * q + 3] * rstd * g0.w); *(u32x2*)(orow + d) = t;
;         t.x = pk2(o1[4 * q] * rstd * g1.x, o1[4 * q + 1] * rstd * g1.y); t.y = pk2(o1[4 * q + 2] * rstd * g1.z, o1[4 * q + 3] * rstd * g1.w); *(u32x2*)(orow + 32 + d) = t; }
.LBB0_676:
	v_lshl_add_u64 v[12:13], s[58:59], 2, v[178:179]
	global_load_dwordx4 v[4:7], v[12:13], off
	global_load_dwordx4 v[8:11], v[12:13], off offset:128
	global_load_dwordx4 v[114:117], v[12:13], off offset:32
	global_load_dwordx4 v[118:121], v[12:13], off offset:160
	global_load_dwordx4 v[122:125], v[12:13], off offset:64
	global_load_dwordx4 v[126:129], v[12:13], off offset:192
	global_load_dwordx4 v[216:219], v[12:13], off offset:96
	global_load_dwordx4 v[158:161], v[12:13], off offset:224
	s_nop 5
	v_mul_f32_e32 v88, v50, v50
	v_mul_f32_e32 v89, v51, v51
	v_mul_f32_e32 v90, v52, v52
	v_fmac_f32_e32 v88, v66, v66
	v_fmac_f32_e32 v89, v67, v67
	v_mul_f32_e32 v91, v53, v53
	v_fmac_f32_e32 v90, v68, v68
	v_add_f32_e32 v88, v88, v89
	v_mul_f32_e32 v92, v54, v54
	v_fmac_f32_e32 v91, v69, v69
	v_add_f32_e32 v88, v90, v88
	v_mul_f32_e32 v93, v55, v55
	v_fmac_f32_e32 v92, v70, v70
	v_add_f32_e32 v88, v91, v88
	v_pk_mul_f32 v[14:15], v[56:57], v[56:57]
	v_fmac_f32_e32 v93, v71, v71
	v_add_f32_e32 v88, v92, v88
	v_pk_fma_f32 v[14:15], v[72:73], v[72:73], v[14:15]
	v_add_f32_e32 v88, v93, v88
	v_pk_mul_f32 v[16:17], v[58:59], v[58:59]
	v_add_f32_e32 v14, v14, v88
	v_pk_fma_f32 v[16:17], v[74:75], v[74:75], v[16:17]
	v_add_f32_e32 v14, v15, v14
	v_pk_mul_f32 v[82:83], v[60:61], v[60:61]
	v_add_f32_e32 v14, v16, v14
	v_pk_fma_f32 v[82:83], v[76:77], v[76:77], v[82:83]
	v_add_f32_e32 v14, v17, v14
	v_pk_mul_f32 v[84:85], v[62:63], v[62:63]
	v_add_f32_e32 v14, v82, v14
	v_pk_fma_f32 v[84:85], v[78:79], v[78:79], v[84:85]
	v_add_f32_e32 v14, v83, v14
	v_pk_mul_f32 v[86:87], v[64:65], v[64:65]
	v_add_f32_e32 v14, v84, v14
	v_pk_fma_f32 v[86:87], v[80:81], v[80:81], v[86:87]
	v_add_f32_e32 v14, v85, v14
	v_add_f32_e32 v14, v86, v14
	v_add_f32_e32 v16, v87, v14
	ds_bpermute_b32 v17, v146, v16
	s_ashr_i32 s0, s92, 10
	s_ashr_i32 s1, s0, 31
	s_lshl_b64 s[0:1], s[0:1], 12
	s_or_b32 s0, s0, s95
	s_waitcnt lgkmcnt(0)
	v_add_f32_e32 v16, v16, v17
	v_fmamk_f32 v16, v16, 0x3c800000, v210
	v_mul_f32_e32 v17, 0x4b800000, v16
	v_cmp_gt_f32_e32 vcc, s56, v16
	v_mov_b32_e32 v15, s1
	v_or_b32_e32 v14, s0, v170
	v_cndmask_b32_e32 v16, v16, v17, vcc
	v_rsq_f32_e32 v16, v16
	v_lshlrev_b64 v[14:15], 11, v[14:15]
	v_lshl_add_u64 v[14:15], s[84:85], 0, v[14:15]
	v_lshlrev_b32_e32 v2, 1, v172
	v_lshl_add_u64 v[14:15], s[58:59], 1, v[14:15]
	v_lshl_add_u64 v[14:15], v[14:15], 0, v[2:3]
	v_mul_f32_e32 v2, 0x45800000, v16
	v_cndmask_b32_e32 v2, v16, v2, vcc
	v_pk_mul_f32 v[16:17], v[66:67], v[2:3] op_sel_hi:[1,0]
	v_pk_mul_f32 v[82:83], v[68:69], v[2:3] op_sel_hi:[1,0]
	v_pk_mul_f32 v[84:85], v[50:51], v[2:3] op_sel_hi:[1,0]
	v_pk_mul_f32 v[86:87], v[52:53], v[2:3] op_sel_hi:[1,0]
	s_add_i32 s92, s92, s54
	s_mov_b32 s81, -1
	s_waitcnt vmcnt(7)
	v_pk_mul_f32 v[4:5], v[4:5], v[16:17]
	v_pk_mul_f32 v[6:7], v[6:7], v[82:83]
	s_waitcnt vmcnt(6)
	v_pk_mul_f32 v[8:9], v[8:9], v[84:85]
	v_pk_mul_f32 v[10:11], v[10:11], v[86:87]
	v_cvt_pk_f16_f32 v4, v4, v5
	v_cvt_pk_f16_f32 v5, v6, v7
	v_cvt_pk_f16_f32 v6, v8, v9
	v_cvt_pk_f16_f32 v7, v10, v11
	global_store_dwordx2 v[14:15], v[4:5], off
	global_store_dwordx2 v[14:15], v[6:7], off offset:64
	s_nop 0
	v_pk_mul_f32 v[16:17], v[70:71], v[2:3] op_sel_hi:[1,0]
	v_pk_mul_f32 v[82:83], v[72:73], v[2:3] op_sel_hi:[1,0]
	v_pk_mul_f32 v[84:85], v[54:55], v[2:3] op_sel_hi:[1,0]
	v_pk_mul_f32 v[86:87], v[56:57], v[2:3] op_sel_hi:[1,0]
	s_waitcnt vmcnt(7)
	v_pk_mul_f32 v[4:5], v[114:115], v[16:17]
	v_pk_mul_f32 v[6:7], v[116:117], v[82:83]
	s_waitcnt vmcnt(6)
	v_pk_mul_f32 v[8:9], v[118:119], v[84:85]
	v_pk_mul_f32 v[10:11], v[120:121], v[86:87]
	v_cvt_pk_f16_f32 v4, v4, v5
	v_cvt_pk_f16_f32 v5, v6, v7
	v_cvt_pk_f16_f32 v6, v8, v9
	v_cvt_pk_f16_f32 v7, v10, v11
	global_store_dwordx2 v[14:15], v[4:5], off offset:16
	global_store_dwordx2 v[14:15], v[6:7], off offset:80
	s_nop 0
	v_pk_mul_f32 v[16:17], v[74:75], v[2:3] op_sel_hi:[1,0]
	v_pk_mul_f32 v[82:83], v[76:77], v[2:3] op_sel_hi:[1,0]
	v_pk_mul_f32 v[84:85], v[58:59], v[2:3] op_sel_hi:[1,0]
	v_pk_mul_f32 v[86:87], v[60:61], v[2:3] op_sel_hi:[1,0]
	s_waitcnt vmcnt(7)
	v_pk_mul_f32 v[4:5], v[16:17], v[122:123]
	v_pk_mul_f32 v[6:7], v[82:83], v[124:125]
	s_waitcnt vmcnt(6)
	v_pk_mul_f32 v[8:9], v[84:85], v[126:127]
	v_pk_mul_f32 v[10:11], v[86:87], v[128:129]
	v_cvt_pk_f16_f32 v4, v4, v5
	v_cvt_pk_f16_f32 v5, v6, v7
	v_cvt_pk_f16_f32 v6, v8, v9
	v_cvt_pk_f16_f32 v7, v10, v11
	global_store_dwordx2 v[14:15], v[4:5], off offset:32
	global_store_dwordx2 v[14:15], v[6:7], off offset:96
	s_nop 0
	v_pk_mul_f32 v[12:13], v[78:79], v[2:3] op_sel_hi:[1,0]
	v_pk_mul_f32 v[16:17], v[80:81], v[2:3] op_sel_hi:[1,0]
	v_pk_mul_f32 v[82:83], v[62:63], v[2:3] op_sel_hi:[1,0]
	v_pk_mul_f32 v[84:85], v[64:65], v[2:3] op_sel_hi:[1,0]
	s_waitcnt vmcnt(7)
	v_pk_mul_f32 v[4:5], v[12:13], v[216:217]
	v_pk_mul_f32 v[6:7], v[16:17], v[218:219]
	s_waitcnt vmcnt(6)
	v_pk_mul_f32 v[8:9], v[82:83], v[158:159]
	v_pk_mul_f32 v[10:11], v[84:85], v[160:161]
	v_cvt_pk_f16_f32 v4, v4, v5
	v_cvt_pk_f16_f32 v5, v6, v7
	v_cvt_pk_f16_f32 v6, v8, v9
	v_cvt_pk_f16_f32 v7, v10, v11
	global_store_dwordx2 v[14:15], v[4:5], off offset:48
	global_store_dwordx2 v[14:15], v[6:7], off offset:112

; __device__ __forceinline__ unsigned pk2(float lo, float hi) { f32x2 v = {lo, hi}; h16x2 b = __builtin_convertvector(v, h16x2); return __builtin_bit_cast(unsigned, b); }
; __device__ __forceinline__ void attn_fin(const Ctx& F, const float* sbg, int bh, int qt, const f32x16& o0, const f32x16& o1) {
;     ...
;     float ss = 0.f;
; #pragma unroll
;     for (int r = 0; r < 16; ++r) ss += o0[r] * o0[r] + o1[r] * o1[r];
;     ss += __shfl_xor(ss, 32);
;     const float rstd = rsqrtf(ss * (1.f / 64.f) + NORM_EPS);
;     const float* sg = sbg + h * 64;
;     bf16* orow = CAT + ((size_t)b * SEQ + qt * 32 + j) * 1024 + h * 64;
; #pragma unroll
;     for (int q = 0; q < 4; ++q) { const int d = 8 * q + 4 * hi; const f32x4 g0 = *(const f32x4*)(sg + d), g1 = *(const f32x4*)(sg + 32 + d);
;         u32x2 t; t.x = pk2(o0[4 * q] * rstd * g0.x, o0[4 * q + 1] * rstd * g0.y); t.y = pk2(o0[4 * q + 2] * rstd * g0.z, o0[4 * q + 3] * rstd * g0.w); *(u32x2*)(orow + d) = t;
;         t.x = pk2(o1[4 * q] * rstd * g1.x, o1[4 * q + 1] * rstd * g1.y); t.y = pk2(o1[4 * q + 2] * rstd * g1.z, o1[4 * q + 3] * rstd * g1.w); *(u32x2*)(orow + 32 + d) = t; }
.LBB0_689:
	v_lshl_add_u64 v[12:13], s[58:59], 2, v[178:179]
	global_load_dwordx4 v[4:7], v[12:13], off
	global_load_dwordx4 v[8:11], v[12:13], off offset:128
	global_load_dwordx4 v[114:117], v[12:13], off offset:32
	global_load_dwordx4 v[118:121], v[12:13], off offset:160
	global_load_dwordx4 v[122:125], v[12:13], off offset:64
	global_load_dwordx4 v[126:129], v[12:13], off offset:192
	global_load_dwordx4 v[140:143], v[12:13], off offset:96
	global_load_dwordx4 v[130:133], v[12:13], off offset:224
	s_nop 5
	v_mul_f32_e32 v88, v50, v50
	v_mul_f32_e32 v89, v51, v51
	v_mul_f32_e32 v90, v52, v52
	v_fmac_f32_e32 v88, v66, v66
	v_fmac_f32_e32 v89, v67, v67
	v_mul_f32_e32 v91, v53, v53
	v_fmac_f32_e32 v90, v68, v68
	v_add_f32_e32 v88, v88, v89
	v_mul_f32_e32 v92, v54, v54
	v_fmac_f32_e32 v91, v69, v69
	v_add_f32_e32 v88, v90, v88
	v_mul_f32_e32 v93, v55, v55
	v_fmac_f32_e32 v92, v70, v70
	v_add_f32_e32 v88, v91, v88
	v_pk_mul_f32 v[14:15], v[56:57], v[56:57]
	v_fmac_f32_e32 v93, v71, v71
	v_add_f32_e32 v88, v92, v88
	v_pk_fma_f32 v[14:15], v[72:73], v[72:73], v[14:15]
	v_add_f32_e32 v88, v93, v88
	v_pk_mul_f32 v[16:17], v[58:59], v[58:59]
	v_add_f32_e32 v14, v14, v88
	v_pk_fma_f32 v[16:17], v[74:75], v[74:75], v[16:17]
	v_add_f32_e32 v14, v15, v14
	v_pk_mul_f32 v[82:83], v[60:61], v[60:61]
	v_add_f32_e32 v14, v16, v14
	v_pk_fma_f32 v[82:83], v[76:77], v[76:77], v[82:83]
	v_add_f32_e32 v14, v17, v14
	v_pk_mul_f32 v[84:85], v[62:63], v[62:63]
	v_add_f32_e32 v14, v82, v14
	v_pk_fma_f32 v[84:85], v[78:79], v[78:79], v[84:85]
	v_add_f32_e32 v14, v83, v14
	v_pk_mul_f32 v[86:87], v[64:65], v[64:65]
	v_add_f32_e32 v14, v84, v14
	v_pk_fma_f32 v[86:87], v[80:81], v[80:81], v[86:87]
	v_add_f32_e32 v14, v85, v14
	v_add_f32_e32 v14, v86, v14
	v_add_f32_e32 v16, v87, v14
	ds_bpermute_b32 v17, v138, v16
	s_ashr_i32 s0, s92, 10
	s_ashr_i32 s1, s0, 31
	s_lshl_b64 s[0:1], s[0:1], 12
	s_or_b32 s0, s0, s88
	s_waitcnt lgkmcnt(0)
	v_add_f32_e32 v16, v16, v17
	v_fmamk_f32 v16, v16, 0x3c800000, v210
	v_mul_f32_e32 v17, 0x4b800000, v16
	v_cmp_gt_f32_e32 vcc, s56, v16
	v_mov_b32_e32 v15, s1
	v_or_b32_e32 v14, s0, v170
	v_cndmask_b32_e32 v16, v16, v17, vcc
	v_rsq_f32_e32 v16, v16
	v_lshlrev_b64 v[14:15], 11, v[14:15]
	v_lshl_add_u64 v[14:15], s[84:85], 0, v[14:15]
	v_lshlrev_b32_e32 v2, 1, v172
	v_lshl_add_u64 v[14:15], s[58:59], 1, v[14:15]
	v_lshl_add_u64 v[14:15], v[14:15], 0, v[2:3]
	v_mul_f32_e32 v2, 0x45800000, v16
	v_cndmask_b32_e32 v2, v16, v2, vcc
	v_pk_mul_f32 v[16:17], v[66:67], v[2:3] op_sel_hi:[1,0]
	v_pk_mul_f32 v[82:83], v[68:69], v[2:3] op_sel_hi:[1,0]
	v_pk_mul_f32 v[84:85], v[50:51], v[2:3] op_sel_hi:[1,0]
	v_pk_mul_f32 v[86:87], v[52:53], v[2:3] op_sel_hi:[1,0]
	s_add_i32 s92, s92, s54
	s_mov_b32 s81, -1
	s_waitcnt vmcnt(7)
	v_pk_mul_f32 v[4:5], v[4:5], v[16:17]
	v_pk_mul_f32 v[6:7], v[6:7], v[82:83]
	s_waitcnt vmcnt(6)
	v_pk_mul_f32 v[8:9], v[8:9], v[84:85]
	v_pk_mul_f32 v[10:11], v[10:11], v[86:87]
	v_cvt_pk_f16_f32 v4, v4, v5
	v_cvt_pk_f16_f32 v5, v6, v7
	v_cvt_pk_f16_f32 v6, v8, v9
	v_cvt_pk_f16_f32 v7, v10, v11
	global_store_dwordx2 v[14:15], v[4:5], off
	global_store_dwordx2 v[14:15], v[6:7], off offset:64
	s_nop 0
	v_pk_mul_f32 v[16:17], v[70:71], v[2:3] op_sel_hi:[1,0]
	v_pk_mul_f32 v[82:83], v[72:73], v[2:3] op_sel_hi:[1,0]
	v_pk_mul_f32 v[84:85], v[54:55], v[2:3] op_sel_hi:[1,0]
	v_pk_mul_f32 v[86:87], v[56:57], v[2:3] op_sel_hi:[1,0]
	s_waitcnt vmcnt(7)
	v_pk_mul_f32 v[4:5], v[114:115], v[16:17]
	v_pk_mul_f32 v[6:7], v[116:117], v[82:83]
	s_waitcnt vmcnt(6)
	v_pk_mul_f32 v[8:9], v[118:119], v[84:85]
	v_pk_mul_f32 v[10:11], v[120:121], v[86:87]
	v_cvt_pk_f16_f32 v4, v4, v5
	v_cvt_pk_f16_f32 v5, v6, v7
	v_cvt_pk_f16_f32 v6, v8, v9
	v_cvt_pk_f16_f32 v7, v10, v11
	global_store_dwordx2 v[14:15], v[4:5], off offset:16
	global_store_dwordx2 v[14:15], v[6:7], off offset:80
	s_nop 0
	v_pk_mul_f32 v[16:17], v[74:75], v[2:3] op_sel_hi:[1,0]
	v_pk_mul_f32 v[82:83], v[76:77], v[2:3] op_sel_hi:[1,0]
	v_pk_mul_f32 v[84:85], v[58:59], v[2:3] op_sel_hi:[1,0]
	v_pk_mul_f32 v[86:87], v[60:61], v[2:3] op_sel_hi:[1,0]
	s_waitcnt vmcnt(7)
	v_pk_mul_f32 v[4:5], v[16:17], v[122:123]
	v_pk_mul_f32 v[6:7], v[82:83], v[124:125]
	s_waitcnt vmcnt(6)
	v_pk_mul_f32 v[8:9], v[84:85], v[126:127]
	v_pk_mul_f32 v[10:11], v[86:87], v[128:129]
	v_cvt_pk_f16_f32 v4, v4, v5
	v_cvt_pk_f16_f32 v5, v6, v7
	v_cvt_pk_f16_f32 v6, v8, v9
	v_cvt_pk_f16_f32 v7, v10, v11
	global_store_dwordx2 v[14:15], v[4:5], off offset:32
	global_store_dwordx2 v[14:15], v[6:7], off offset:96
	s_nop 0
	v_pk_mul_f32 v[12:13], v[78:79], v[2:3] op_sel_hi:[1,0]
	v_pk_mul_f32 v[16:17], v[80:81], v[2:3] op_sel_hi:[1,0]
	v_pk_mul_f32 v[82:83], v[62:63], v[2:3] op_sel_hi:[1,0]
	v_pk_mul_f32 v[84:85], v[64:65], v[2:3] op_sel_hi:[1,0]
	s_waitcnt vmcnt(7)
	v_pk_mul_f32 v[4:5], v[12:13], v[140:141]
	v_pk_mul_f32 v[6:7], v[16:17], v[142:143]
	s_waitcnt vmcnt(6)
	v_pk_mul_f32 v[8:9], v[82:83], v[130:131]
	v_pk_mul_f32 v[10:11], v[84:85], v[132:133]
	v_cvt_pk_f16_f32 v4, v4, v5
	v_cvt_pk_f16_f32 v5, v6, v7
	v_cvt_pk_f16_f32 v6, v8, v9
	v_cvt_pk_f16_f32 v7, v10, v11
	global_store_dwordx2 v[14:15], v[4:5], off offset:48
	global_store_dwordx2 v[14:15], v[6:7], off offset:112
	s_branch .LBB0_681

; __device__ __forceinline__ unsigned cvt_pk_bf16(float lo, float hi) { unsigned r; asm volatile("v_cvt_pk_f16_f32 %0, %1, %2" : "=v"(r) : "v"(lo), "v"(hi)); return r; }
;     __device__ __forceinline__ void operator()(const f32x4 (&acc)[2][2][4][2], const Unit& u, int wr, int wc, int fr, int fq) const {
;         const int row0 = u.pm * BM + wr * 64 + fr, col0 = u.pn * HALF + wc * 32 + 8 * fq;
; #pragma unroll
;         for (int ai = 0; ai < 2; ++ai)
; #pragma unroll
;             for (int m = 0; m < 4; ++m) {
;                 const int row = row0 + ai * HALF + m * 16; const float sc = rs[row];
;                 const float sc2 = sc * sc, nsl = -1.4426950408889634f * sc;
;                 bf16_t* rowp = O + (size_t)row * ldc + col0;
;                 float h[8];
; #pragma unroll
;                 for (int n = 0; n < 2; ++n)
; #pragma unroll
;                     for (int e = 0; e < 4; ++e) { const float g = acc[ai][0][m][n][e], up = acc[ai][1][m][n][e];
;                         h[4 * n + e] = (g * up) * (sc2 * __builtin_amdgcn_rcpf(1.0f + __builtin_amdgcn_exp2f(g * nsl))); }
;                 u32x4 w; w.x = cvt_pk_bf16(h[0], h[1]); w.y = cvt_pk_bf16(h[2], h[3]); w.z = cvt_pk_bf16(h[4], h[5]); w.w = cvt_pk_bf16(h[6], h[7]);
;                 *(u32x4*)rowp = w;
;             }
.LBB0_1017:
	v_lshl_add_u32 v146, s22, 8, v1
	v_ashrrev_i32_e32 v147, 31, v146
	v_lshl_add_u64 v[150:151], v[146:147], 2, s[8:9]
	global_load_dword v147, v[150:151], off
	global_load_dword v192, v[150:151], off offset:64
	global_load_dword v194, v[150:151], off offset:128
	global_load_dword v196, v[150:151], off offset:192
	global_load_dword v198, v[150:151], off offset:512
	global_load_dword v200, v[150:151], off offset:576
	global_load_dword v202, v[150:151], off offset:640
	global_load_dword v204, v[150:151], off offset:704
	v_mov_b32_e32 v172, v125
	v_mov_b32_e32 v160, v118
	v_mov_b32_e32 v164, v127
	v_mov_b32_e32 v166, v129
	v_lshl_or_b32 v158, s47, 7, v153
	v_mov_b64_e32 v[148:149], s[6:7]
	v_ashrrev_i32_e32 v159, 31, v158
	v_or_b32_e32 v176, 16, v146
	v_mov_b32_e32 v168, v122
	v_mov_b32_e32 v170, v123
	v_mad_i64_i32 v[174:175], s[24:25], v146, s46, v[148:149]
	v_lshlrev_b64 v[122:123], 1, v[158:159]
	v_ashrrev_i32_e32 v177, 31, v176
	v_lshl_add_u64 v[158:159], v[174:175], 0, v[122:123]
	v_lshl_add_u64 v[174:175], v[176:177], 2, s[8:9]
	s_andn2_b64 vcc, exec, s[2:3]
	s_mov_b64 s[2:3], -1
	s_waitcnt vmcnt(0)
	v_mul_f32_e32 v125, 0xbfb8aa3b, v147
	v_mul_f32_e32 v118, v118, v125
	v_mul_f32_e32 v127, v119, v125
	v_exp_f32_e32 v118, v118
	v_mul_f32_e32 v129, v120, v125
	v_mul_f32_e32 v165, v115, v125
	v_exp_f32_e32 v127, v127
	v_mul_f32_e32 v161, v147, v147
	v_mul_f32_e32 v147, v121, v125
	v_exp_f32_e32 v129, v129
	v_exp_f32_e32 v165, v165
	v_mul_f32_e32 v157, v114, v125
	v_mul_f32_e32 v167, v116, v125
	v_exp_f32_e32 v147, v147
	v_exp_f32_e32 v157, v157
	v_exp_f32_e32 v167, v167
	v_add_f32_e32 v118, 1.0, v118
	v_add_f32_e32 v169, 1.0, v127
	v_rcp_f32_e32 v127, v118
	v_mul_f32_e32 v125, v117, v125
	v_add_f32_e32 v129, 1.0, v129
	v_add_f32_e32 v171, 1.0, v165
	v_rcp_f32_e32 v165, v169
	v_exp_f32_e32 v125, v125
	v_add_f32_e32 v147, 1.0, v147
	v_rcp_f32_e32 v129, v129
	v_add_f32_e32 v157, 1.0, v157
	v_add_f32_e32 v173, 1.0, v167
	v_rcp_f32_e32 v167, v147
	v_rcp_f32_e32 v169, v157
	v_pk_mul_f32 v[126:127], v[160:161], v[126:127]
	v_mov_b32_e32 v160, v119
	v_rcp_f32_e32 v171, v171
	v_pk_mul_f32 v[118:119], v[160:161], v[164:165]
	v_mov_b32_e32 v160, v120
	v_add_f32_e32 v177, 1.0, v125
	v_rcp_f32_e32 v125, v173
	v_mul_f32_e32 v120, v118, v119
	v_pk_mul_f32 v[118:119], v[160:161], v[128:129]
	v_mov_b32_e32 v160, v121
	v_rcp_f32_e32 v173, v177
	v_mul_f32_e32 v121, v118, v119
	v_pk_mul_f32 v[118:119], v[160:161], v[166:167]
	v_mov_b32_e32 v160, v114
	v_mul_f32_e32 v126, v126, v127
	v_cvt_pk_f16_f32 v114, v126, v120
	v_mul_f32_e32 v120, v118, v119
	v_pk_mul_f32 v[118:119], v[160:161], v[168:169]
	v_mov_b32_e32 v160, v115
	v_mul_f32_e32 v126, v118, v119
	v_pk_mul_f32 v[118:119], v[160:161], v[170:171]
	v_mov_b32_e32 v160, v116
	v_mul_f32_e32 v116, v118, v119
	v_pk_mul_f32 v[118:119], v[160:161], v[124:125]
	v_mov_b32_e32 v160, v117
	v_mul_f32_e32 v117, v118, v119
	v_pk_mul_f32 v[118:119], v[160:161], v[172:173]
	v_cvt_pk_f16_f32 v115, v121, v120
	v_cvt_pk_f16_f32 v116, v126, v116
	v_mov_b32_e32 v120, v107
	v_mul_f32_e32 v118, v118, v119
	v_cvt_pk_f16_f32 v117, v117, v118
	global_store_dwordx4 v[158:159], v[114:117], off
	s_nop 0
	v_mov_b32_e32 v124, v109
	v_mov_b32_e32 v114, v102
	v_mov_b32_e32 v116, v111
	v_mov_b32_e32 v118, v113
	v_or_b32_e32 v126, 32, v146
	v_ashrrev_i32_e32 v127, 31, v126
	v_lshl_add_u64 v[158:159], v[126:127], 2, s[8:9]
	v_mad_i64_i32 v[128:129], s[24:25], v176, s46, v[148:149]
	v_lshl_add_u64 v[128:129], v[128:129], 0, v[122:123]
	v_mul_f32_e32 v107, 0xbfb8aa3b, v192
	v_mul_f32_e32 v102, v102, v107
	v_mul_f32_e32 v109, v103, v107
	v_mul_f32_e32 v111, v104, v107
	v_exp_f32_e32 v102, v102
	v_mul_f32_e32 v115, v192, v192
	v_mul_f32_e32 v117, v98, v107
	v_exp_f32_e32 v109, v109
	v_exp_f32_e32 v111, v111
	v_mul_f32_e32 v113, v105, v107
	v_exp_f32_e32 v117, v117
	v_mul_f32_e32 v119, v99, v107
	v_exp_f32_e32 v113, v113
	v_mul_f32_e32 v121, v100, v107
	v_mul_f32_e32 v107, v101, v107
	v_exp_f32_e32 v119, v119
	v_add_f32_e32 v102, 1.0, v102
	v_exp_f32_e32 v107, v107
	v_add_f32_e32 v109, 1.0, v109
	v_add_f32_e32 v125, 1.0, v111
	v_rcp_f32_e32 v111, v102
	v_exp_f32_e32 v121, v121
	v_add_f32_e32 v147, 1.0, v117
	v_rcp_f32_e32 v117, v109
	v_add_f32_e32 v127, 1.0, v113
	v_rcp_f32_e32 v113, v125
	v_add_f32_e32 v157, 1.0, v119
	v_rcp_f32_e32 v119, v127
	v_add_f32_e32 v161, 1.0, v107
	v_rcp_f32_e32 v107, v147
	v_pk_mul_f32 v[110:111], v[114:115], v[110:111]
	v_mov_b32_e32 v114, v103
	v_add_f32_e32 v160, 1.0, v121
	v_rcp_f32_e32 v121, v157
	v_pk_mul_f32 v[102:103], v[114:115], v[116:117]
	v_mov_b32_e32 v114, v104
	v_rcp_f32_e32 v109, v160
	v_mul_f32_e32 v104, v102, v103
	v_pk_mul_f32 v[102:103], v[114:115], v[112:113]
	v_mov_b32_e32 v114, v105
	v_rcp_f32_e32 v125, v161
	v_mul_f32_e32 v105, v102, v103
	v_pk_mul_f32 v[102:103], v[114:115], v[118:119]
	v_mov_b32_e32 v114, v98
	v_mul_f32_e32 v110, v110, v111
	v_cvt_pk_f16_f32 v98, v110, v104
	v_mul_f32_e32 v104, v102, v103
	v_pk_mul_f32 v[102:103], v[114:115], v[106:107]
	v_mov_b32_e32 v114, v99
	v_mul_f32_e32 v106, v102, v103
	v_pk_mul_f32 v[102:103], v[114:115], v[120:121]
	v_mov_b32_e32 v114, v100
	v_mul_f32_e32 v100, v102, v103
	v_pk_mul_f32 v[102:103], v[114:115], v[108:109]
	v_mov_b32_e32 v114, v101
	v_mul_f32_e32 v101, v102, v103
	v_pk_mul_f32 v[102:103], v[114:115], v[124:125]
	v_cvt_pk_f16_f32 v99, v105, v104
	v_cvt_pk_f16_f32 v100, v106, v100
	v_mov_b32_e32 v104, v91
	v_mul_f32_e32 v102, v102, v103
	v_cvt_pk_f16_f32 v101, v101, v102
	global_store_dwordx4 v[128:129], v[98:101], off
	s_nop 0
	v_mov_b32_e32 v106, v93
	v_mov_b32_e32 v98, v86
	v_mov_b32_e32 v100, v95
	v_mov_b32_e32 v102, v97
; __device__ __forceinline__ unsigned cvt_pk_bf16(float lo, float hi) { unsigned r; asm volatile("v_cvt_pk_f16_f32 %0, %1, %2" : "=v"(r) : "v"(lo), "v"(hi)); return r; }
;     __device__ __forceinline__ void operator()(const f32x4 (&acc)[2][2][4][2], const Unit& u, int wr, int wc, int fr, int fq) const {
;     ...
;                 const int row = row0 + ai * HALF + m * 16; const float sc = rs[row];
;                 const float sc2 = sc * sc, nsl = -1.4426950408889634f * sc;
;                 bf16_t* rowp = O + (size_t)row * ldc + col0;
;                 float h[8];
; #pragma unroll
;                 for (int n = 0; n < 2; ++n)
; #pragma unroll
;                     for (int e = 0; e < 4; ++e) { const float g = acc[ai][0][m][n][e], up = acc[ai][1][m][n][e];
;                         h[4 * n + e] = (g * up) * (sc2 * __builtin_amdgcn_rcpf(1.0f + __builtin_amdgcn_exp2f(g * nsl))); }
;                 u32x4 w; w.x = cvt_pk_bf16(h[0], h[1]); w.y = cvt_pk_bf16(h[2], h[3]); w.z = cvt_pk_bf16(h[4], h[5]); w.w = cvt_pk_bf16(h[6], h[7]);
;                 *(u32x4*)rowp = w;
	v_or_b32_e32 v108, 48, v146
	v_ashrrev_i32_e32 v109, 31, v108
	v_lshl_add_u64 v[112:113], v[108:109], 2, s[8:9]
	v_mad_i64_i32 v[110:111], s[24:25], v126, s46, v[148:149]
	v_lshl_add_u64 v[110:111], v[110:111], 0, v[122:123]
	v_mul_f32_e32 v91, 0xbfb8aa3b, v194
	v_mul_f32_e32 v86, v86, v91
	v_mul_f32_e32 v93, v87, v91
	v_mul_f32_e32 v95, v88, v91
	v_exp_f32_e32 v86, v86
	v_mul_f32_e32 v99, v194, v194
	v_mul_f32_e32 v101, v82, v91
	v_exp_f32_e32 v93, v93
	v_exp_f32_e32 v95, v95
	v_mul_f32_e32 v97, v89, v91
	v_exp_f32_e32 v101, v101
	v_mul_f32_e32 v103, v83, v91
	v_exp_f32_e32 v97, v97
	v_mul_f32_e32 v105, v84, v91
	v_mul_f32_e32 v91, v85, v91
	v_exp_f32_e32 v103, v103
	v_add_f32_e32 v86, 1.0, v86
	v_exp_f32_e32 v91, v91
	v_add_f32_e32 v93, 1.0, v93
	v_add_f32_e32 v107, 1.0, v95
	v_rcp_f32_e32 v95, v86
	v_exp_f32_e32 v105, v105
	v_add_f32_e32 v114, 1.0, v101
	v_rcp_f32_e32 v101, v93
	v_add_f32_e32 v109, 1.0, v97
	v_rcp_f32_e32 v97, v107
	v_add_f32_e32 v115, 1.0, v103
	v_rcp_f32_e32 v103, v109
	v_add_f32_e32 v117, 1.0, v91
	v_rcp_f32_e32 v91, v114
	v_pk_mul_f32 v[94:95], v[98:99], v[94:95]
	v_mov_b32_e32 v98, v87
	v_add_f32_e32 v116, 1.0, v105
	v_rcp_f32_e32 v105, v115
	v_pk_mul_f32 v[86:87], v[98:99], v[100:101]
	v_mov_b32_e32 v98, v88
	v_rcp_f32_e32 v93, v116
	v_mul_f32_e32 v88, v86, v87
	v_pk_mul_f32 v[86:87], v[98:99], v[96:97]
	v_mov_b32_e32 v98, v89
	v_rcp_f32_e32 v107, v117
	v_mul_f32_e32 v89, v86, v87
	v_pk_mul_f32 v[86:87], v[98:99], v[102:103]
	v_mov_b32_e32 v98, v82
	v_mul_f32_e32 v94, v94, v95
	v_cvt_pk_f16_f32 v82, v94, v88
	v_mul_f32_e32 v88, v86, v87
	v_pk_mul_f32 v[86:87], v[98:99], v[90:91]
	v_mov_b32_e32 v98, v83
	v_mul_f32_e32 v90, v86, v87
	v_pk_mul_f32 v[86:87], v[98:99], v[104:105]
	v_mov_b32_e32 v98, v84
	v_mul_f32_e32 v84, v86, v87
	v_pk_mul_f32 v[86:87], v[98:99], v[92:93]
	v_mov_b32_e32 v98, v85
	v_mul_f32_e32 v85, v86, v87
	v_pk_mul_f32 v[86:87], v[98:99], v[106:107]
	v_cvt_pk_f16_f32 v83, v89, v88
	v_cvt_pk_f16_f32 v84, v90, v84
	v_mov_b32_e32 v88, v75
	v_mul_f32_e32 v86, v86, v87
	v_cvt_pk_f16_f32 v85, v85, v86
	global_store_dwordx4 v[110:111], v[82:85], off
	s_nop 0
	v_mov_b32_e32 v90, v77
	v_mov_b32_e32 v82, v70
	v_mov_b32_e32 v84, v79
	v_mov_b32_e32 v86, v81
	v_mad_i64_i32 v[92:93], s[24:25], v108, s46, v[148:149]
	v_lshl_add_u64 v[92:93], v[92:93], 0, v[122:123]
	v_mul_f32_e32 v75, 0xbfb8aa3b, v196
	v_mul_f32_e32 v70, v70, v75
	v_mul_f32_e32 v77, v71, v75
	v_mul_f32_e32 v79, v72, v75
	v_exp_f32_e32 v70, v70
	v_mul_f32_e32 v83, v196, v196
	v_mul_f32_e32 v85, v66, v75
	v_exp_f32_e32 v77, v77
	v_exp_f32_e32 v79, v79
	v_mul_f32_e32 v81, v73, v75
	v_exp_f32_e32 v85, v85
	v_mul_f32_e32 v87, v67, v75
	v_exp_f32_e32 v81, v81
	v_mul_f32_e32 v89, v68, v75
	v_mul_f32_e32 v75, v69, v75
	v_exp_f32_e32 v87, v87
	v_add_f32_e32 v70, 1.0, v70
	v_exp_f32_e32 v75, v75
	v_add_f32_e32 v77, 1.0, v77
	v_add_f32_e32 v91, 1.0, v79
	v_rcp_f32_e32 v79, v70
	v_exp_f32_e32 v89, v89
	v_add_f32_e32 v95, 1.0, v85
	v_rcp_f32_e32 v85, v77
	v_add_f32_e32 v94, 1.0, v81
	v_rcp_f32_e32 v81, v91
	v_add_f32_e32 v96, 1.0, v87
	v_rcp_f32_e32 v87, v94
	v_add_f32_e32 v98, 1.0, v75
	v_rcp_f32_e32 v75, v95
	v_pk_mul_f32 v[78:79], v[82:83], v[78:79]
	v_mov_b32_e32 v82, v71
	v_add_f32_e32 v97, 1.0, v89
	v_rcp_f32_e32 v89, v96
	v_pk_mul_f32 v[70:71], v[82:83], v[84:85]
	v_mov_b32_e32 v82, v72
	v_rcp_f32_e32 v77, v97
	v_mul_f32_e32 v72, v70, v71
	v_pk_mul_f32 v[70:71], v[82:83], v[80:81]
	v_mov_b32_e32 v82, v73
	v_rcp_f32_e32 v91, v98
	v_mul_f32_e32 v73, v70, v71
	v_pk_mul_f32 v[70:71], v[82:83], v[86:87]
	v_mov_b32_e32 v82, v66
	v_mul_f32_e32 v78, v78, v79
	v_cvt_pk_f16_f32 v66, v78, v72
	v_mul_f32_e32 v72, v70, v71
	v_pk_mul_f32 v[70:71], v[82:83], v[74:75]
	v_mov_b32_e32 v82, v67
	v_mul_f32_e32 v74, v70, v71
	v_pk_mul_f32 v[70:71], v[82:83], v[88:89]
	v_mov_b32_e32 v82, v68
	v_mul_f32_e32 v68, v70, v71
	v_pk_mul_f32 v[70:71], v[82:83], v[76:77]
	v_mov_b32_e32 v82, v69
	v_mul_f32_e32 v69, v70, v71
	v_pk_mul_f32 v[70:71], v[82:83], v[90:91]
	v_cvt_pk_f16_f32 v67, v73, v72
	v_cvt_pk_f16_f32 v68, v74, v68
	v_mov_b32_e32 v72, v59
	v_mul_f32_e32 v70, v70, v71
	v_cvt_pk_f16_f32 v69, v69, v70
	global_store_dwordx4 v[92:93], v[66:69], off
	s_nop 0
	v_add_u32_e32 v59, 0x80, v146
	v_mad_i64_i32 v[76:77], s[24:25], v59, s46, v[148:149]
	v_mov_b32_e32 v66, v54
	v_mov_b32_e32 v68, v63
	v_mov_b32_e32 v74, v61
	v_mov_b32_e32 v70, v65
	v_lshl_add_u64 v[76:77], v[76:77], 0, v[122:123]
	v_mul_f32_e32 v59, 0xbfb8aa3b, v198
	v_mul_f32_e32 v54, v54, v59
	v_mul_f32_e32 v61, v55, v59
	v_mul_f32_e32 v63, v56, v59
	v_exp_f32_e32 v54, v54
	v_mul_f32_e32 v67, v198, v198
	v_mul_f32_e32 v69, v50, v59
	v_exp_f32_e32 v61, v61
	v_exp_f32_e32 v63, v63
	v_mul_f32_e32 v65, v57, v59
	v_exp_f32_e32 v69, v69
	v_mul_f32_e32 v71, v51, v59
	v_exp_f32_e32 v65, v65
	v_mul_f32_e32 v73, v52, v59
	v_mul_f32_e32 v59, v53, v59
	v_exp_f32_e32 v71, v71
	v_add_f32_e32 v54, 1.0, v54
	v_exp_f32_e32 v59, v59
	v_add_f32_e32 v61, 1.0, v61
	v_add_f32_e32 v75, 1.0, v63
	v_rcp_f32_e32 v63, v54
	v_exp_f32_e32 v73, v73
	v_add_f32_e32 v79, 1.0, v69
	v_rcp_f32_e32 v69, v61
	v_add_f32_e32 v78, 1.0, v65
	v_rcp_f32_e32 v65, v75
	v_add_f32_e32 v80, 1.0, v71
	v_rcp_f32_e32 v71, v78
	v_add_f32_e32 v82, 1.0, v59
	v_rcp_f32_e32 v59, v79
	v_pk_mul_f32 v[62:63], v[66:67], v[62:63]
	v_mov_b32_e32 v66, v55
	v_add_f32_e32 v81, 1.0, v73
	v_rcp_f32_e32 v73, v80
	v_pk_mul_f32 v[54:55], v[66:67], v[68:69]
	v_mov_b32_e32 v66, v56
	v_rcp_f32_e32 v61, v81
	v_mul_f32_e32 v56, v54, v55
	v_pk_mul_f32 v[54:55], v[66:67], v[64:65]
	v_mov_b32_e32 v66, v57
	v_rcp_f32_e32 v75, v82
	v_mul_f32_e32 v57, v54, v55
	v_pk_mul_f32 v[54:55], v[66:67], v[70:71]
; __device__ __forceinline__ unsigned cvt_pk_bf16(float lo, float hi) { unsigned r; asm volatile("v_cvt_pk_f16_f32 %0, %1, %2" : "=v"(r) : "v"(lo), "v"(hi)); return r; }
;     __device__ __forceinline__ void operator()(const f32x4 (&acc)[2][2][4][2], const Unit& u, int wr, int wc, int fr, int fq) const {
;     ...
;                 const int row = row0 + ai * HALF + m * 16; const float sc = rs[row];
;                 const float sc2 = sc * sc, nsl = -1.4426950408889634f * sc;
;                 bf16_t* rowp = O + (size_t)row * ldc + col0;
;                 float h[8];
; #pragma unroll
;                 for (int n = 0; n < 2; ++n)
; #pragma unroll
;                     for (int e = 0; e < 4; ++e) { const float g = acc[ai][0][m][n][e], up = acc[ai][1][m][n][e];
;                         h[4 * n + e] = (g * up) * (sc2 * __builtin_amdgcn_rcpf(1.0f + __builtin_amdgcn_exp2f(g * nsl))); }
;                 u32x4 w; w.x = cvt_pk_bf16(h[0], h[1]); w.y = cvt_pk_bf16(h[2], h[3]); w.z = cvt_pk_bf16(h[4], h[5]); w.w = cvt_pk_bf16(h[6], h[7]);
;                 *(u32x4*)rowp = w;
	v_mov_b32_e32 v66, v50
	v_mul_f32_e32 v62, v62, v63
	v_cvt_pk_f16_f32 v50, v62, v56
	v_mul_f32_e32 v56, v54, v55
	v_pk_mul_f32 v[54:55], v[66:67], v[58:59]
	v_mov_b32_e32 v66, v51
	v_mul_f32_e32 v58, v54, v55
	v_pk_mul_f32 v[54:55], v[66:67], v[72:73]
	v_mov_b32_e32 v66, v52
	v_mul_f32_e32 v52, v54, v55
	v_pk_mul_f32 v[54:55], v[66:67], v[60:61]
	v_mov_b32_e32 v66, v53
	v_mul_f32_e32 v53, v54, v55
	v_pk_mul_f32 v[54:55], v[66:67], v[74:75]
	v_cvt_pk_f16_f32 v51, v57, v56
	v_cvt_pk_f16_f32 v52, v58, v52
	v_mov_b32_e32 v56, v43
	v_mul_f32_e32 v54, v54, v55
	v_cvt_pk_f16_f32 v53, v53, v54
	global_store_dwordx4 v[76:77], v[50:53], off
	s_nop 0
	v_add_u32_e32 v43, 0x90, v146
	v_mad_i64_i32 v[60:61], s[24:25], v43, s46, v[148:149]
	v_mov_b32_e32 v50, v38
	v_mov_b32_e32 v52, v47
	v_mov_b32_e32 v58, v45
	v_mov_b32_e32 v54, v49
	v_lshl_add_u64 v[60:61], v[60:61], 0, v[122:123]
	v_mul_f32_e32 v43, 0xbfb8aa3b, v200
	v_mul_f32_e32 v38, v38, v43
	v_mul_f32_e32 v45, v39, v43
	v_mul_f32_e32 v47, v40, v43
	v_exp_f32_e32 v38, v38
	v_mul_f32_e32 v51, v200, v200
	v_mul_f32_e32 v53, v34, v43
	v_exp_f32_e32 v45, v45
	v_exp_f32_e32 v47, v47
	v_mul_f32_e32 v49, v41, v43
	v_exp_f32_e32 v53, v53
	v_mul_f32_e32 v55, v35, v43
	v_exp_f32_e32 v49, v49
	v_mul_f32_e32 v57, v36, v43
	v_mul_f32_e32 v43, v37, v43
	v_exp_f32_e32 v55, v55
	v_add_f32_e32 v38, 1.0, v38
	v_exp_f32_e32 v43, v43
	v_add_f32_e32 v45, 1.0, v45
	v_add_f32_e32 v59, 1.0, v47
	v_rcp_f32_e32 v47, v38
	v_exp_f32_e32 v57, v57
	v_add_f32_e32 v63, 1.0, v53
	v_rcp_f32_e32 v53, v45
	v_add_f32_e32 v62, 1.0, v49
	v_rcp_f32_e32 v49, v59
	v_add_f32_e32 v64, 1.0, v55
	v_rcp_f32_e32 v55, v62
	v_add_f32_e32 v66, 1.0, v43
	v_rcp_f32_e32 v43, v63
	v_pk_mul_f32 v[46:47], v[50:51], v[46:47]
	v_mov_b32_e32 v50, v39
	v_add_f32_e32 v65, 1.0, v57
	v_rcp_f32_e32 v57, v64
	v_pk_mul_f32 v[38:39], v[50:51], v[52:53]
	v_mov_b32_e32 v50, v40
	v_rcp_f32_e32 v45, v65
	v_mul_f32_e32 v40, v38, v39
	v_pk_mul_f32 v[38:39], v[50:51], v[48:49]
	v_mov_b32_e32 v50, v41
	v_rcp_f32_e32 v59, v66
	v_mul_f32_e32 v41, v38, v39
	v_pk_mul_f32 v[38:39], v[50:51], v[54:55]
	v_mov_b32_e32 v50, v34
	v_mul_f32_e32 v46, v46, v47
	v_cvt_pk_f16_f32 v34, v46, v40
	v_mul_f32_e32 v40, v38, v39
	v_pk_mul_f32 v[38:39], v[50:51], v[42:43]
	v_mov_b32_e32 v50, v35
	v_mul_f32_e32 v42, v38, v39
	v_pk_mul_f32 v[38:39], v[50:51], v[56:57]
	v_mov_b32_e32 v50, v36
	v_mul_f32_e32 v36, v38, v39
	v_pk_mul_f32 v[38:39], v[50:51], v[44:45]
	v_mov_b32_e32 v50, v37
	v_mul_f32_e32 v37, v38, v39
	v_pk_mul_f32 v[38:39], v[50:51], v[58:59]
	v_cvt_pk_f16_f32 v35, v41, v40
	v_cvt_pk_f16_f32 v36, v42, v36
	v_mov_b32_e32 v40, v27
	v_mul_f32_e32 v38, v38, v39
	v_cvt_pk_f16_f32 v37, v37, v38
	global_store_dwordx4 v[60:61], v[34:37], off
	s_nop 0
	v_add_u32_e32 v27, 0xa0, v146
	v_mad_i64_i32 v[44:45], s[24:25], v27, s46, v[148:149]
	v_mov_b32_e32 v34, v22
	v_mov_b32_e32 v36, v31
	v_mov_b32_e32 v42, v29
	v_mov_b32_e32 v38, v33
	v_lshl_add_u64 v[44:45], v[44:45], 0, v[122:123]
	v_mul_f32_e32 v27, 0xbfb8aa3b, v202
	v_mul_f32_e32 v22, v22, v27
	v_mul_f32_e32 v29, v23, v27
	v_mul_f32_e32 v31, v24, v27
	v_exp_f32_e32 v22, v22
	v_mul_f32_e32 v35, v202, v202
	v_mul_f32_e32 v37, v18, v27
	v_exp_f32_e32 v29, v29
	v_exp_f32_e32 v31, v31
	v_mul_f32_e32 v33, v25, v27
	v_exp_f32_e32 v37, v37
	v_mul_f32_e32 v39, v19, v27
	v_exp_f32_e32 v33, v33
	v_mul_f32_e32 v41, v20, v27
	v_mul_f32_e32 v27, v21, v27
	v_exp_f32_e32 v39, v39
	v_add_f32_e32 v22, 1.0, v22
	v_exp_f32_e32 v27, v27
	v_add_f32_e32 v29, 1.0, v29
	v_add_f32_e32 v43, 1.0, v31
	v_rcp_f32_e32 v31, v22
	v_exp_f32_e32 v41, v41
	v_add_f32_e32 v47, 1.0, v37
	v_rcp_f32_e32 v37, v29
	v_add_f32_e32 v46, 1.0, v33
	v_rcp_f32_e32 v33, v43
	v_add_f32_e32 v48, 1.0, v39
	v_rcp_f32_e32 v39, v46
	v_add_f32_e32 v50, 1.0, v27
	v_rcp_f32_e32 v27, v47
	v_pk_mul_f32 v[30:31], v[34:35], v[30:31]
	v_mov_b32_e32 v34, v23
	v_add_f32_e32 v49, 1.0, v41
	v_rcp_f32_e32 v41, v48
	v_pk_mul_f32 v[22:23], v[34:35], v[36:37]
	v_mov_b32_e32 v34, v24
	v_rcp_f32_e32 v29, v49
	v_mul_f32_e32 v24, v22, v23
	v_pk_mul_f32 v[22:23], v[34:35], v[32:33]
	v_mov_b32_e32 v34, v25
	v_rcp_f32_e32 v43, v50
	v_mul_f32_e32 v25, v22, v23
	v_pk_mul_f32 v[22:23], v[34:35], v[38:39]
	v_mov_b32_e32 v34, v18
	v_mul_f32_e32 v30, v30, v31
	v_cvt_pk_f16_f32 v18, v30, v24
	v_mul_f32_e32 v24, v22, v23
	v_pk_mul_f32 v[22:23], v[34:35], v[26:27]
	v_mov_b32_e32 v34, v19
	v_mul_f32_e32 v26, v22, v23
	v_pk_mul_f32 v[22:23], v[34:35], v[40:41]
	v_mov_b32_e32 v34, v20
	v_mul_f32_e32 v20, v22, v23
	v_pk_mul_f32 v[22:23], v[34:35], v[28:29]
	v_mov_b32_e32 v34, v21
	v_mul_f32_e32 v21, v22, v23
	v_pk_mul_f32 v[22:23], v[34:35], v[42:43]
	v_cvt_pk_f16_f32 v19, v25, v24
	v_cvt_pk_f16_f32 v20, v26, v20
	v_mov_b32_e32 v24, v11
	v_mul_f32_e32 v22, v22, v23
	v_cvt_pk_f16_f32 v21, v21, v22
	global_store_dwordx4 v[44:45], v[18:21], off
	s_nop 0
	v_add_u32_e32 v11, 0xb0, v146
	v_mad_i64_i32 v[28:29], s[24:25], v11, s46, v[148:149]
	v_mov_b32_e32 v18, v6
	v_mov_b32_e32 v20, v15
	v_mov_b32_e32 v26, v13
	v_mov_b32_e32 v22, v17
	v_lshl_add_u64 v[28:29], v[28:29], 0, v[122:123]
	v_mul_f32_e32 v11, 0xbfb8aa3b, v204
	v_mul_f32_e32 v6, v6, v11
	v_mul_f32_e32 v13, v7, v11
	v_mul_f32_e32 v15, v8, v11
	v_exp_f32_e32 v6, v6
	v_mul_f32_e32 v19, v204, v204
	v_mul_f32_e32 v21, v2, v11
	v_exp_f32_e32 v13, v13
	v_exp_f32_e32 v15, v15
	v_mul_f32_e32 v17, v9, v11
	v_exp_f32_e32 v21, v21
	v_mul_f32_e32 v23, v3, v11
	v_exp_f32_e32 v17, v17
	v_mul_f32_e32 v25, v4, v11
	v_mul_f32_e32 v11, v5, v11
	v_exp_f32_e32 v23, v23
	v_add_f32_e32 v6, 1.0, v6
	v_exp_f32_e32 v11, v11
	v_add_f32_e32 v13, 1.0, v13
	v_add_f32_e32 v27, 1.0, v15
	v_rcp_f32_e32 v15, v6
	v_exp_f32_e32 v25, v25
	v_add_f32_e32 v31, 1.0, v21
	v_rcp_f32_e32 v21, v13
	v_add_f32_e32 v30, 1.0, v17
	v_rcp_f32_e32 v17, v27
	v_add_f32_e32 v32, 1.0, v23
	v_rcp_f32_e32 v23, v30
	v_add_f32_e32 v34, 1.0, v11
	v_rcp_f32_e32 v11, v31
	v_pk_mul_f32 v[14:15], v[18:19], v[14:15]
	v_mov_b32_e32 v18, v7
	v_add_f32_e32 v33, 1.0, v25
	v_rcp_f32_e32 v25, v32
	v_pk_mul_f32 v[6:7], v[18:19], v[20:21]
	v_mov_b32_e32 v18, v8
	v_rcp_f32_e32 v13, v33
	v_mul_f32_e32 v8, v6, v7
	v_pk_mul_f32 v[6:7], v[18:19], v[16:17]
	v_mov_b32_e32 v18, v9
	v_rcp_f32_e32 v27, v34
	v_mul_f32_e32 v9, v6, v7
	v_pk_mul_f32 v[6:7], v[18:19], v[22:23]
	v_mov_b32_e32 v18, v2
	v_mul_f32_e32 v14, v14, v15
	v_cvt_pk_f16_f32 v2, v14, v8
	v_mul_f32_e32 v8, v6, v7
	v_pk_mul_f32 v[6:7], v[18:19], v[10:11]
	v_mov_b32_e32 v18, v3
	v_mul_f32_e32 v10, v6, v7
	v_pk_mul_f32 v[6:7], v[18:19], v[24:25]
	v_mov_b32_e32 v18, v4
	v_mul_f32_e32 v4, v6, v7
	v_pk_mul_f32 v[6:7], v[18:19], v[12:13]
	v_mov_b32_e32 v18, v5
	v_mul_f32_e32 v5, v6, v7
	v_pk_mul_f32 v[6:7], v[18:19], v[26:27]
	v_cvt_pk_f16_f32 v3, v9, v8
	v_cvt_pk_f16_f32 v4, v10, v4
	s_nop 0
	v_mul_f32_e32 v6, v6, v7
	v_cvt_pk_f16_f32 v5, v5, v6
	global_store_dwordx4 v[28:29], v[2:5], off
	s_cbranch_vccnz .LBB0_1010
	s_andn2_b64 vcc, exec, s[4:5]
	s_cbranch_vccnz .LBB0_1009
	s_barrier
	s_branch .LBB0_1009
